# phases 2,7,8,10: post-loop vmcnt(0) removed so the epilogue loads issue while the last prefetch DMAs are still landing (the epilogue load waits cover them in order)
# speedup vs baseline: 1.0024x; 1.0024x over previous
; #define PG8_STAGE(bufoff, gbase, voff) do { _Pragma("unroll") for (int _i = 0; _i < 2; ++_i) \
;         __builtin_amdgcn_global_load_lds((const unsigned*)((const char*)(gbase) + (voff)[_i]), (LAS unsigned*)(lds + (bufoff) + ldsw + _i * 8192), 16, 0, 0); } while (0)
; #define PG8_LDA(dst, b, h) do { _Pragma("unroll") for (int m = 0; m < 4; ++m) _Pragma("unroll") for (int k = 0; k < 2; ++k) dst[m][k] = *(const LAS bf16x8*)(lds + PG8_SA(b, h) + aoff + m * 2048 + k * 1024); } while (0)
; #define PG8_LDB(dst, b, h) do { _Pragma("unroll") for (int n = 0; n < 2; ++n) _Pragma("unroll") for (int k = 0; k < 2; ++k) dst[n][k] = *(const LAS bf16x8*)(lds + PG8_SB(b, h) + boff + n * 2048 + k * 1024); } while (0)
; #define PG8_MMA(ai, bj, At, Bt) do { __builtin_amdgcn_s_setprio(1); _Pragma("unroll") for (int m = 0; m < 4; ++m) _Pragma("unroll") for (int n = 0; n < 2; ++n) _Pragma("unroll") for (int k = 0; k < 2; ++k) \
;         acc[ai][bj][m][n] = __builtin_amdgcn_mfma_f32_16x16x32_bf16(Bt[n][k], At[m][k], acc[ai][bj][m][n], 0, 0, 0); __builtin_amdgcn_s_setprio(0); } while (0)
; #define PG8_WAIT_V(n) asm volatile("s_waitcnt vmcnt(" #n ")" ::: "memory")
; #define PG8_WAIT_L(n) asm volatile("s_waitcnt lgkmcnt(" #n ")" ::: "memory")
; #define PG8_BAR __builtin_amdgcn_s_barrier()
; #define PG8_SCHED __builtin_amdgcn_sched_barrier(0)
; template <class Epi, class Sched>
; DI void gemm_phase(LAS unsigned char* lds, const Gemm g, const Sched& S, const Epi& E) {
;     ...
;             PG8_LDB(B0, 0, 0); PG8_LDB(B1, 0, 1); PG8_SCHED; PG8_LDA(At, 0, 0); PG8_STAGE(PG8_SA(1, 1), a1 + hstepA, voffA);
;             PG8_WAIT_V(8); PG8_WAIT_L(0); PG8_BAR; PG8_MMA(0, 0, At, B0); PG8_MMA(0, 1, At, B1); PG8_BAR; PG8_SCHED;
;             PG8_LDA(At, 0, 1); PG8_STAGE(PG8_SB(0, 0), b2, voffB); PG8_STAGE(PG8_SB(0, 1), b2 + hstepB, voffB); PG8_STAGE(PG8_SA(0, 0), a2, voffA);
;             PG8_WAIT_V(8); PG8_WAIT_L(0); PG8_BAR; PG8_MMA(1, 0, At, B0); PG8_MMA(1, 1, At, B1); PG8_BAR; PG8_SCHED;
.LBB0_278:
	ds_read_b128 v[148:151], v154
	ds_read_b128 v[158:161], v154 offset:1024
	ds_read_b128 v[162:165], v154 offset:2048
	ds_read_b128 v[166:169], v154 offset:3072
	ds_read_b128 v[170:173], v155
	ds_read_b128 v[174:177], v155 offset:1024
	ds_read_b128 v[178:181], v155 offset:2048
	ds_read_b128 v[186:189], v155 offset:3072
	s_add_u32 s38, s36, 0xfff50080
	s_addc_u32 s39, s37, -1
	s_cmp_eq_u32 s62, 40
	s_cselect_b32 s41, s9, s39
	s_cselect_b32 s40, s8, s38
	s_cselect_b32 s39, s35, s61
	s_cselect_b32 s38, s34, s60
	v_lshl_add_u64 v[182:183], s[36:37], 0, v[138:139]
	s_add_i32 m0, s45, 0xc000
	ds_read_b128 v[190:193], v156
	ds_read_b128 v[194:197], v156 offset:1024
	ds_read_b128 v[198:201], v156 offset:2048
	ds_read_b128 v[202:205], v156 offset:3072
	ds_read_b128 v[206:209], v156 offset:4096
	ds_read_b128 v[210:213], v156 offset:5120
	ds_read_b128 v[214:217], v156 offset:6144
	ds_read_b128 v[218:221], v156 offset:7168
	global_load_lds_dwordx4 v[182:183], off
	v_lshl_add_u64 v[182:183], s[36:37], 0, v[140:141]
	s_add_i32 m0, s45, 0xe000
	s_nop 0
	global_load_lds_dwordx4 v[182:183], off
	s_waitcnt vmcnt(8)
	s_waitcnt lgkmcnt(0)
	s_barrier
	s_setprio 1
	v_mfma_f32_16x16x32_bf16 v[126:129], v[148:151], v[190:193], v[126:129]
	v_mfma_f32_16x16x32_bf16 v[122:125], v[162:165], v[190:193], v[122:125]
	v_mfma_f32_16x16x32_bf16 v[110:113], v[148:151], v[198:201], v[110:113]
	v_mfma_f32_16x16x32_bf16 v[106:109], v[162:165], v[198:201], v[106:109]
	v_mfma_f32_16x16x32_bf16 v[94:97], v[148:151], v[206:209], v[94:97]
	v_mfma_f32_16x16x32_bf16 v[90:93], v[162:165], v[206:209], v[90:93]
	v_mfma_f32_16x16x32_bf16 v[78:81], v[148:151], v[214:217], v[78:81]
	v_mfma_f32_16x16x32_bf16 v[74:77], v[162:165], v[214:217], v[74:77]
	v_mfma_f32_16x16x32_bf16 v[126:129], v[158:161], v[194:197], v[126:129]
	v_mfma_f32_16x16x32_bf16 v[122:125], v[166:169], v[194:197], v[122:125]
	v_mfma_f32_16x16x32_bf16 v[110:113], v[158:161], v[202:205], v[110:113]
	v_mfma_f32_16x16x32_bf16 v[106:109], v[166:169], v[202:205], v[106:109]
	v_mfma_f32_16x16x32_bf16 v[94:97], v[158:161], v[210:213], v[94:97]
	v_mfma_f32_16x16x32_bf16 v[90:93], v[166:169], v[210:213], v[90:93]
	v_mfma_f32_16x16x32_bf16 v[78:81], v[158:161], v[218:221], v[78:81]
	v_mfma_f32_16x16x32_bf16 v[74:77], v[166:169], v[218:221], v[74:77]
	v_mfma_f32_16x16x32_bf16 v[118:121], v[170:173], v[190:193], v[118:121]
	v_mfma_f32_16x16x32_bf16 v[114:117], v[178:181], v[190:193], v[114:117]
	v_mfma_f32_16x16x32_bf16 v[102:105], v[170:173], v[198:201], v[102:105]
	v_mfma_f32_16x16x32_bf16 v[98:101], v[178:181], v[198:201], v[98:101]
	v_mfma_f32_16x16x32_bf16 v[86:89], v[170:173], v[206:209], v[86:89]
	v_mfma_f32_16x16x32_bf16 v[82:85], v[178:181], v[206:209], v[82:85]
	v_mfma_f32_16x16x32_bf16 v[70:73], v[170:173], v[214:217], v[70:73]
	v_mfma_f32_16x16x32_bf16 v[66:69], v[178:181], v[214:217], v[66:69]
	v_mfma_f32_16x16x32_bf16 v[118:121], v[174:177], v[194:197], v[118:121]
	v_mfma_f32_16x16x32_bf16 v[114:117], v[186:189], v[194:197], v[114:117]
	v_mfma_f32_16x16x32_bf16 v[102:105], v[174:177], v[202:205], v[102:105]
	v_mfma_f32_16x16x32_bf16 v[98:101], v[186:189], v[202:205], v[98:101]
	v_mfma_f32_16x16x32_bf16 v[86:89], v[174:177], v[210:213], v[86:89]
	v_mfma_f32_16x16x32_bf16 v[82:85], v[186:189], v[210:213], v[82:85]
	v_mfma_f32_16x16x32_bf16 v[70:73], v[174:177], v[218:221], v[70:73]
	v_mfma_f32_16x16x32_bf16 v[66:69], v[186:189], v[218:221], v[66:69]
	s_setprio 0
	s_barrier
	s_add_i32 s63, s54, s44
	v_lshl_add_u64 v[182:183], s[38:39], 0, v[132:133]
	s_mov_b32 m0, s63
	ds_read_b128 v[190:193], v156 offset:16384
	ds_read_b128 v[194:197], v156 offset:17408
	ds_read_b128 v[198:201], v156 offset:18432
	ds_read_b128 v[202:205], v156 offset:19456
	ds_read_b128 v[206:209], v156 offset:20480
	ds_read_b128 v[210:213], v156 offset:21504
	ds_read_b128 v[214:217], v156 offset:22528
	ds_read_b128 v[218:221], v156 offset:23552
	global_load_lds_dwordx4 v[182:183], off
	s_add_i32 m0, s63, 0x2000
	s_add_u32 s64, s38, 0xb0000
	v_lshl_add_u64 v[222:223], s[38:39], 0, v[136:137]
	s_addc_u32 s65, s39, 0
	s_add_i32 s63, s55, s44
	global_load_lds_dwordx4 v[222:223], off
	v_lshl_add_u64 v[224:225], s[64:65], 0, v[132:133]
	s_mov_b32 m0, s63
	v_lshl_add_u64 v[226:227], s[40:41], 0, v[134:135]
	global_load_lds_dwordx4 v[224:225], off
	v_lshl_add_u64 v[224:225], s[64:65], 0, v[136:137]
	s_add_i32 m0, s63, 0x2000
	s_nop 0
	global_load_lds_dwordx4 v[224:225], off
	v_lshl_add_u64 v[224:225], s[40:41], 0, v[130:131]
	s_mov_b32 m0, s45
	s_nop 0
	global_load_lds_dwordx4 v[224:225], off
	s_mov_b32 m0, s46
	s_nop 0
	global_load_lds_dwordx4 v[226:227], off
	s_waitcnt vmcnt(8)
	s_waitcnt lgkmcnt(0)
	s_barrier
; #define PG8_STAGE(bufoff, gbase, voff) do { _Pragma("unroll") for (int _i = 0; _i < 2; ++_i) \
;         __builtin_amdgcn_global_load_lds((const unsigned*)((const char*)(gbase) + (voff)[_i]), (LAS unsigned*)(lds + (bufoff) + ldsw + _i * 8192), 16, 0, 0); } while (0)
; #define PG8_LDA(dst, b, h) do { _Pragma("unroll") for (int m = 0; m < 4; ++m) _Pragma("unroll") for (int k = 0; k < 2; ++k) dst[m][k] = *(const LAS bf16x8*)(lds + PG8_SA(b, h) + aoff + m * 2048 + k * 1024); } while (0)
; #define PG8_LDB(dst, b, h) do { _Pragma("unroll") for (int n = 0; n < 2; ++n) _Pragma("unroll") for (int k = 0; k < 2; ++k) dst[n][k] = *(const LAS bf16x8*)(lds + PG8_SB(b, h) + boff + n * 2048 + k * 1024); } while (0)
; #define PG8_MMA(ai, bj, At, Bt) do { __builtin_amdgcn_s_setprio(1); _Pragma("unroll") for (int m = 0; m < 4; ++m) _Pragma("unroll") for (int n = 0; n < 2; ++n) _Pragma("unroll") for (int k = 0; k < 2; ++k) \
;         acc[ai][bj][m][n] = __builtin_amdgcn_mfma_f32_16x16x32_bf16(Bt[n][k], At[m][k], acc[ai][bj][m][n], 0, 0, 0); __builtin_amdgcn_s_setprio(0); } while (0)
; #define PG8_WAIT_V(n) asm volatile("s_waitcnt vmcnt(" #n ")" ::: "memory")
; #define PG8_WAIT_L(n) asm volatile("s_waitcnt lgkmcnt(" #n ")" ::: "memory")
; #define PG8_BAR __builtin_amdgcn_s_barrier()
; #define PG8_SCHED __builtin_amdgcn_sched_barrier(0)
; template <class Epi, class Sched>
; DI void gemm_phase(LAS unsigned char* lds, const Gemm g, const Sched& S, const Epi& E) {
;     ...
;             PG8_WAIT_V(8); PG8_WAIT_L(0); PG8_BAR; PG8_MMA(1, 0, At, B0); PG8_MMA(1, 1, At, B1); PG8_BAR; PG8_SCHED;
;             PG8_LDB(B0, 1, 0); PG8_LDB(B1, 1, 1); PG8_SCHED; PG8_LDA(At, 1, 0); PG8_STAGE(PG8_SA(0, 1), a2 + hstepA, voffA);
;             PG8_WAIT_V(8); PG8_WAIT_L(0); PG8_BAR; PG8_MMA(0, 0, At, B0); PG8_MMA(0, 1, At, B1); PG8_BAR; PG8_SCHED;
	s_setprio 1
	v_mfma_f32_16x16x32_bf16 v[62:65], v[148:151], v[190:193], v[62:65]
	v_mfma_f32_16x16x32_bf16 v[58:61], v[162:165], v[190:193], v[58:61]
	v_mfma_f32_16x16x32_bf16 v[46:49], v[148:151], v[198:201], v[46:49]
	v_mfma_f32_16x16x32_bf16 v[42:45], v[162:165], v[198:201], v[42:45]
	v_mfma_f32_16x16x32_bf16 v[30:33], v[148:151], v[206:209], v[30:33]
	v_mfma_f32_16x16x32_bf16 v[26:29], v[162:165], v[206:209], v[26:29]
	v_mfma_f32_16x16x32_bf16 v[14:17], v[148:151], v[214:217], v[14:17]
	v_mfma_f32_16x16x32_bf16 v[10:13], v[162:165], v[214:217], v[10:13]
	v_mfma_f32_16x16x32_bf16 v[62:65], v[158:161], v[194:197], v[62:65]
	v_mfma_f32_16x16x32_bf16 v[58:61], v[166:169], v[194:197], v[58:61]
	v_mfma_f32_16x16x32_bf16 v[46:49], v[158:161], v[202:205], v[46:49]
	v_mfma_f32_16x16x32_bf16 v[42:45], v[166:169], v[202:205], v[42:45]
	v_mfma_f32_16x16x32_bf16 v[30:33], v[158:161], v[210:213], v[30:33]
	v_mfma_f32_16x16x32_bf16 v[26:29], v[166:169], v[210:213], v[26:29]
	v_mfma_f32_16x16x32_bf16 v[14:17], v[158:161], v[218:221], v[14:17]
	v_mfma_f32_16x16x32_bf16 v[10:13], v[166:169], v[218:221], v[10:13]
	v_mfma_f32_16x16x32_bf16 v[54:57], v[170:173], v[190:193], v[54:57]
	v_mfma_f32_16x16x32_bf16 v[50:53], v[178:181], v[190:193], v[50:53]
	v_mfma_f32_16x16x32_bf16 v[38:41], v[170:173], v[198:201], v[38:41]
	v_mfma_f32_16x16x32_bf16 v[34:37], v[178:181], v[198:201], v[34:37]
	v_mfma_f32_16x16x32_bf16 v[22:25], v[170:173], v[206:209], v[22:25]
	v_mfma_f32_16x16x32_bf16 v[18:21], v[178:181], v[206:209], v[18:21]
	v_mfma_f32_16x16x32_bf16 v[6:9], v[170:173], v[214:217], v[6:9]
	v_mfma_f32_16x16x32_bf16 v[2:5], v[178:181], v[214:217], v[2:5]
	v_mfma_f32_16x16x32_bf16 v[54:57], v[174:177], v[194:197], v[54:57]
	v_mfma_f32_16x16x32_bf16 v[50:53], v[186:189], v[194:197], v[50:53]
	v_mfma_f32_16x16x32_bf16 v[38:41], v[174:177], v[202:205], v[38:41]
	v_mfma_f32_16x16x32_bf16 v[34:37], v[186:189], v[202:205], v[34:37]
	v_mfma_f32_16x16x32_bf16 v[22:25], v[174:177], v[210:213], v[22:25]
	v_mfma_f32_16x16x32_bf16 v[18:21], v[186:189], v[210:213], v[18:21]
	v_mfma_f32_16x16x32_bf16 v[6:9], v[174:177], v[218:221], v[6:9]
	v_mfma_f32_16x16x32_bf16 v[2:5], v[186:189], v[218:221], v[2:5]
	s_setprio 0
	s_barrier
	s_add_i32 s63, 0, 0x18000
	s_add_i32 s64, 0, 0x1c000
	v_add_u32_e32 v166, s63, v152
	v_add_u32_e32 v185, s64, v152
	ds_read_b128 v[148:151], v166
	ds_read_b128 v[158:161], v166 offset:1024
	ds_read_b128 v[162:165], v166 offset:2048
	ds_read_b128 v[166:169], v166 offset:3072
	ds_read_b128 v[170:173], v185
	ds_read_b128 v[174:177], v185 offset:1024
	ds_read_b128 v[178:181], v185 offset:2048
	ds_read_b128 v[186:189], v185 offset:3072
	s_add_u32 s40, s40, 0xb0000
	s_addc_u32 s41, s41, 0
	s_mov_b32 m0, s47
	v_lshl_add_u64 v[228:229], s[40:41], 0, v[130:131]
	ds_read_b128 v[190:193], v156 offset:32768
	ds_read_b128 v[194:197], v156 offset:33792
	ds_read_b128 v[198:201], v156 offset:34816
	ds_read_b128 v[202:205], v156 offset:35840
	ds_read_b128 v[206:209], v156 offset:36864
	ds_read_b128 v[210:213], v156 offset:37888
	ds_read_b128 v[214:217], v156 offset:38912
	ds_read_b128 v[218:221], v156 offset:39936
	global_load_lds_dwordx4 v[228:229], off
	v_lshl_add_u64 v[228:229], s[40:41], 0, v[134:135]
	s_mov_b32 m0, s48
	s_nop 0
	global_load_lds_dwordx4 v[228:229], off
	s_waitcnt vmcnt(8)
	s_waitcnt lgkmcnt(0)
	s_barrier
	s_setprio 1
	v_mfma_f32_16x16x32_bf16 v[126:129], v[148:151], v[190:193], v[126:129]
	v_mfma_f32_16x16x32_bf16 v[122:125], v[162:165], v[190:193], v[122:125]
	v_mfma_f32_16x16x32_bf16 v[110:113], v[148:151], v[198:201], v[110:113]
	v_mfma_f32_16x16x32_bf16 v[106:109], v[162:165], v[198:201], v[106:109]
	v_mfma_f32_16x16x32_bf16 v[94:97], v[148:151], v[206:209], v[94:97]
	v_mfma_f32_16x16x32_bf16 v[90:93], v[162:165], v[206:209], v[90:93]
	v_mfma_f32_16x16x32_bf16 v[78:81], v[148:151], v[214:217], v[78:81]
	v_mfma_f32_16x16x32_bf16 v[74:77], v[162:165], v[214:217], v[74:77]
	v_mfma_f32_16x16x32_bf16 v[126:129], v[158:161], v[194:197], v[126:129]
	v_mfma_f32_16x16x32_bf16 v[122:125], v[166:169], v[194:197], v[122:125]
	v_mfma_f32_16x16x32_bf16 v[110:113], v[158:161], v[202:205], v[110:113]
	v_mfma_f32_16x16x32_bf16 v[106:109], v[166:169], v[202:205], v[106:109]
	v_mfma_f32_16x16x32_bf16 v[94:97], v[158:161], v[210:213], v[94:97]
	v_mfma_f32_16x16x32_bf16 v[90:93], v[166:169], v[210:213], v[90:93]
	v_mfma_f32_16x16x32_bf16 v[78:81], v[158:161], v[218:221], v[78:81]
	v_mfma_f32_16x16x32_bf16 v[74:77], v[166:169], v[218:221], v[74:77]
	v_mfma_f32_16x16x32_bf16 v[118:121], v[170:173], v[190:193], v[118:121]
	v_mfma_f32_16x16x32_bf16 v[114:117], v[178:181], v[190:193], v[114:117]
	v_mfma_f32_16x16x32_bf16 v[102:105], v[170:173], v[198:201], v[102:105]
	v_mfma_f32_16x16x32_bf16 v[98:101], v[178:181], v[198:201], v[98:101]
	v_mfma_f32_16x16x32_bf16 v[86:89], v[170:173], v[206:209], v[86:89]
	v_mfma_f32_16x16x32_bf16 v[82:85], v[178:181], v[206:209], v[82:85]
	v_mfma_f32_16x16x32_bf16 v[70:73], v[170:173], v[214:217], v[70:73]
	v_mfma_f32_16x16x32_bf16 v[66:69], v[178:181], v[214:217], v[66:69]
	v_mfma_f32_16x16x32_bf16 v[118:121], v[174:177], v[194:197], v[118:121]
	v_mfma_f32_16x16x32_bf16 v[114:117], v[186:189], v[194:197], v[114:117]
	v_mfma_f32_16x16x32_bf16 v[102:105], v[174:177], v[202:205], v[102:105]
	v_mfma_f32_16x16x32_bf16 v[98:101], v[186:189], v[202:205], v[98:101]
	v_mfma_f32_16x16x32_bf16 v[86:89], v[174:177], v[210:213], v[86:89]
	v_mfma_f32_16x16x32_bf16 v[82:85], v[186:189], v[210:213], v[82:85]
	v_mfma_f32_16x16x32_bf16 v[70:73], v[174:177], v[218:221], v[70:73]
	v_mfma_f32_16x16x32_bf16 v[66:69], v[186:189], v[218:221], v[66:69]
	s_setprio 0
	s_barrier
; #define PG8_STAGE(bufoff, gbase, voff) do { _Pragma("unroll") for (int _i = 0; _i < 2; ++_i) \
;         __builtin_amdgcn_global_load_lds((const unsigned*)((const char*)(gbase) + (voff)[_i]), (LAS unsigned*)(lds + (bufoff) + ldsw + _i * 8192), 16, 0, 0); } while (0)
; #define PG8_LDA(dst, b, h) do { _Pragma("unroll") for (int m = 0; m < 4; ++m) _Pragma("unroll") for (int k = 0; k < 2; ++k) dst[m][k] = *(const LAS bf16x8*)(lds + PG8_SA(b, h) + aoff + m * 2048 + k * 1024); } while (0)
; #define PG8_MMA(ai, bj, At, Bt) do { __builtin_amdgcn_s_setprio(1); _Pragma("unroll") for (int m = 0; m < 4; ++m) _Pragma("unroll") for (int n = 0; n < 2; ++n) _Pragma("unroll") for (int k = 0; k < 2; ++k) \
;         acc[ai][bj][m][n] = __builtin_amdgcn_mfma_f32_16x16x32_bf16(Bt[n][k], At[m][k], acc[ai][bj][m][n], 0, 0, 0); __builtin_amdgcn_s_setprio(0); } while (0)
; #define PG8_WAIT_V(n) asm volatile("s_waitcnt vmcnt(" #n ")" ::: "memory")
; #define PG8_WAIT_L(n) asm volatile("s_waitcnt lgkmcnt(" #n ")" ::: "memory")
; #define PG8_BAR __builtin_amdgcn_s_barrier()
; #define PG8_SCHED __builtin_amdgcn_sched_barrier(0)
;     DI void pre(Pre& pr, const pg8::Unit& u, int wr, int fr) const { load_rows(pr, ssq, u, wr, fr); }
;     DI void pre(Pre& pr, const pg8::Unit& u, int wr, int fr) const { load_rows(pr, ssq, u, wr, fr); }
; template <class Epi, class Sched>
; DI void gemm_phase(LAS unsigned char* lds, const Gemm g, const Sched& S, const Epi& E) {
;     ...
;             PG8_LDA(At, 1, 1); PG8_STAGE(PG8_SB(1, 0), b3, voffB); PG8_STAGE(PG8_SB(1, 1), b3 + hstepB, voffB); PG8_STAGE(PG8_SA(1, 0), a3, voffA);
;             PG8_WAIT_V(8); PG8_WAIT_L(0); PG8_BAR; PG8_MMA(1, 0, At, B0); PG8_MMA(1, 1, At, B1); PG8_BAR; PG8_SCHED;
;         }
;         if (wr == 0) PG8_BAR;
;         E(acc, cur, wr, wc, fr, fq, pre);
	s_add_i32 s40, s63, s44
	v_lshl_add_u64 v[182:183], v[182:183], 0, s[16:17]
	s_mov_b32 m0, s40
	ds_read_b128 v[190:193], v156 offset:49152
	ds_read_b128 v[194:197], v156 offset:50176
	ds_read_b128 v[198:201], v156 offset:51200
	ds_read_b128 v[202:205], v156 offset:52224
	ds_read_b128 v[206:209], v156 offset:53248
	ds_read_b128 v[210:213], v156 offset:54272
	ds_read_b128 v[214:217], v156 offset:55296
	ds_read_b128 v[218:221], v156 offset:56320
	global_load_lds_dwordx4 v[182:183], off
	s_add_i32 m0, s40, 0x2000
	s_add_u32 s38, s38, 0xb0080
	v_lshl_add_u64 v[182:183], v[222:223], 0, s[16:17]
	s_addc_u32 s39, s39, 0
	s_add_i32 s40, s64, s44
	global_load_lds_dwordx4 v[182:183], off
	v_lshl_add_u64 v[182:183], s[38:39], 0, v[132:133]
	s_mov_b32 m0, s40
	s_nop 0
	global_load_lds_dwordx4 v[182:183], off
	v_lshl_add_u64 v[182:183], s[38:39], 0, v[136:137]
	s_add_i32 m0, s40, 0x2000
	s_nop 0
	global_load_lds_dwordx4 v[182:183], off
	v_lshl_add_u64 v[182:183], v[224:225], 0, s[16:17]
	s_mov_b32 m0, s50
	s_nop 0
	global_load_lds_dwordx4 v[182:183], off
	v_lshl_add_u64 v[182:183], v[226:227], 0, s[16:17]
	s_mov_b32 m0, s51
	s_nop 0
	global_load_lds_dwordx4 v[182:183], off
	s_waitcnt vmcnt(8)
	s_waitcnt lgkmcnt(0)
	s_barrier
	s_setprio 1
	v_mfma_f32_16x16x32_bf16 v[62:65], v[148:151], v[190:193], v[62:65]
	v_mfma_f32_16x16x32_bf16 v[58:61], v[162:165], v[190:193], v[58:61]
	v_mfma_f32_16x16x32_bf16 v[46:49], v[148:151], v[198:201], v[46:49]
	v_mfma_f32_16x16x32_bf16 v[42:45], v[162:165], v[198:201], v[42:45]
	v_mfma_f32_16x16x32_bf16 v[30:33], v[148:151], v[206:209], v[30:33]
	v_mfma_f32_16x16x32_bf16 v[26:29], v[162:165], v[206:209], v[26:29]
	v_mfma_f32_16x16x32_bf16 v[14:17], v[148:151], v[214:217], v[14:17]
	v_mfma_f32_16x16x32_bf16 v[10:13], v[162:165], v[214:217], v[10:13]
	v_mfma_f32_16x16x32_bf16 v[62:65], v[158:161], v[194:197], v[62:65]
	v_mfma_f32_16x16x32_bf16 v[58:61], v[166:169], v[194:197], v[58:61]
	v_mfma_f32_16x16x32_bf16 v[46:49], v[158:161], v[202:205], v[46:49]
	v_mfma_f32_16x16x32_bf16 v[42:45], v[166:169], v[202:205], v[42:45]
	v_mfma_f32_16x16x32_bf16 v[30:33], v[158:161], v[210:213], v[30:33]
	v_mfma_f32_16x16x32_bf16 v[26:29], v[166:169], v[210:213], v[26:29]
	v_mfma_f32_16x16x32_bf16 v[14:17], v[158:161], v[218:221], v[14:17]
	v_mfma_f32_16x16x32_bf16 v[10:13], v[166:169], v[218:221], v[10:13]
	v_mfma_f32_16x16x32_bf16 v[54:57], v[170:173], v[190:193], v[54:57]
	v_mfma_f32_16x16x32_bf16 v[50:53], v[178:181], v[190:193], v[50:53]
	v_mfma_f32_16x16x32_bf16 v[38:41], v[170:173], v[198:201], v[38:41]
	v_mfma_f32_16x16x32_bf16 v[34:37], v[178:181], v[198:201], v[34:37]
	v_mfma_f32_16x16x32_bf16 v[22:25], v[170:173], v[206:209], v[22:25]
	v_mfma_f32_16x16x32_bf16 v[18:21], v[178:181], v[206:209], v[18:21]
	v_mfma_f32_16x16x32_bf16 v[6:9], v[170:173], v[214:217], v[6:9]
	v_mfma_f32_16x16x32_bf16 v[2:5], v[178:181], v[214:217], v[2:5]
	v_mfma_f32_16x16x32_bf16 v[54:57], v[174:177], v[194:197], v[54:57]
	v_mfma_f32_16x16x32_bf16 v[50:53], v[186:189], v[194:197], v[50:53]
	v_mfma_f32_16x16x32_bf16 v[38:41], v[174:177], v[202:205], v[38:41]
	v_mfma_f32_16x16x32_bf16 v[34:37], v[186:189], v[202:205], v[34:37]
	v_mfma_f32_16x16x32_bf16 v[22:25], v[174:177], v[210:213], v[22:25]
	v_mfma_f32_16x16x32_bf16 v[18:21], v[186:189], v[210:213], v[18:21]
	v_mfma_f32_16x16x32_bf16 v[6:9], v[174:177], v[218:221], v[6:9]
	v_mfma_f32_16x16x32_bf16 v[2:5], v[186:189], v[218:221], v[2:5]
	s_setprio 0
	s_barrier
	s_add_i32 s62, s62, 2
	s_add_u32 s36, s36, 0x100
	s_addc_u32 s37, s37, 0
	s_add_u32 s60, s60, 0x100
	s_addc_u32 s61, s61, 0
	s_cmp_gt_u32 s62, 41
	s_cbranch_scc0 .LBB0_278
	s_mov_b32 s99, 1
	s_and_b64 vcc, exec, s[18:19]
	s_cbranch_vccz .LBB0_281
	s_barrier

; #define PG8_STAGE(bufoff, gbase, voff) do { _Pragma("unroll") for (int _i = 0; _i < 2; ++_i) \
;         __builtin_amdgcn_global_load_lds((const unsigned*)((const char*)(gbase) + (voff)[_i]), (LAS unsigned*)(lds + (bufoff) + ldsw + _i * 8192), 16, 0, 0); } while (0)
; #define PG8_LDA(dst, b, h) do { _Pragma("unroll") for (int m = 0; m < 4; ++m) _Pragma("unroll") for (int k = 0; k < 2; ++k) dst[m][k] = *(const LAS bf16x8*)(lds + PG8_SA(b, h) + aoff + m * 2048 + k * 1024); } while (0)
; #define PG8_LDB(dst, b, h) do { _Pragma("unroll") for (int n = 0; n < 2; ++n) _Pragma("unroll") for (int k = 0; k < 2; ++k) dst[n][k] = *(const LAS bf16x8*)(lds + PG8_SB(b, h) + boff + n * 2048 + k * 1024); } while (0)
; #define PG8_MMA(ai, bj, At, Bt) do { __builtin_amdgcn_s_setprio(1); _Pragma("unroll") for (int m = 0; m < 4; ++m) _Pragma("unroll") for (int n = 0; n < 2; ++n) _Pragma("unroll") for (int k = 0; k < 2; ++k) \
;         acc[ai][bj][m][n] = __builtin_amdgcn_mfma_f32_16x16x32_bf16(Bt[n][k], At[m][k], acc[ai][bj][m][n], 0, 0, 0); __builtin_amdgcn_s_setprio(0); } while (0)
; #define PG8_WAIT_V(n) asm volatile("s_waitcnt vmcnt(" #n ")" ::: "memory")
; #define PG8_WAIT_L(n) asm volatile("s_waitcnt lgkmcnt(" #n ")" ::: "memory")
; #define PG8_BAR __builtin_amdgcn_s_barrier()
; #define PG8_SCHED __builtin_amdgcn_sched_barrier(0)
; template <class Epi, class Sched>
; DI void gemm_phase(LAS unsigned char* lds, const Gemm g, const Sched& S, const Epi& E) {
;     ...
;             PG8_LDB(B0, 0, 0); PG8_LDB(B1, 0, 1); PG8_SCHED; PG8_LDA(At, 0, 0); PG8_STAGE(PG8_SA(1, 1), a1 + hstepA, voffA);
;             PG8_WAIT_V(8); PG8_WAIT_L(0); PG8_BAR; PG8_MMA(0, 0, At, B0); PG8_MMA(0, 1, At, B1); PG8_BAR; PG8_SCHED;
;             PG8_LDA(At, 0, 1); PG8_STAGE(PG8_SB(0, 0), b2, voffB); PG8_STAGE(PG8_SB(0, 1), b2 + hstepB, voffB); PG8_STAGE(PG8_SA(0, 0), a2, voffA);
;             PG8_WAIT_V(8); PG8_WAIT_L(0); PG8_BAR; PG8_MMA(1, 0, At, B0); PG8_MMA(1, 1, At, B1); PG8_BAR; PG8_SCHED;
.LBB0_972:
	v_add_u32_e32 v158, s64, v162
	v_add_u32_e32 v180, s65, v162
	ds_read_b128 v[146:149], v158
	ds_read_b128 v[150:153], v158 offset:1024
	ds_read_b128 v[154:157], v158 offset:2048
	ds_read_b128 v[158:161], v158 offset:3072
	ds_read_b128 v[168:171], v180
	ds_read_b128 v[172:175], v180 offset:1024
	ds_read_b128 v[176:179], v180 offset:2048
	ds_read_b128 v[180:183], v180 offset:3072
	s_add_u32 s46, s44, 0xfffe0080
	s_addc_u32 s47, s45, -1
	s_cmp_eq_u32 s72, 4
	s_cselect_b32 s49, s39, s47
	s_cselect_b32 s48, s68, s46
	s_cselect_b32 s47, s37, s71
	s_cselect_b32 s46, s69, s70
	v_lshl_add_u64 v[218:219], s[44:45], 0, v[138:139]
	s_add_i32 m0, s53, 0xc000
	ds_read_b128 v[186:189], v167
	ds_read_b128 v[190:193], v167 offset:1024
	ds_read_b128 v[194:197], v167 offset:2048
	ds_read_b128 v[198:201], v167 offset:3072
	ds_read_b128 v[202:205], v167 offset:4096
	ds_read_b128 v[206:209], v167 offset:5120
	ds_read_b128 v[210:213], v167 offset:6144
	ds_read_b128 v[214:217], v167 offset:7168
	global_load_lds_dwordx4 v[218:219], off
	v_lshl_add_u64 v[218:219], s[44:45], 0, v[140:141]
	s_add_i32 m0, s53, 0xe000
	s_nop 0
	global_load_lds_dwordx4 v[218:219], off
	s_waitcnt vmcnt(8)
	s_waitcnt lgkmcnt(0)
	s_barrier
	s_setprio 1
	v_mfma_f32_16x16x32_bf16 v[126:129], v[146:149], v[186:189], v[126:129]
	v_mfma_f32_16x16x32_bf16 v[122:125], v[154:157], v[186:189], v[122:125]
	v_mfma_f32_16x16x32_bf16 v[118:121], v[146:149], v[194:197], v[118:121]
	v_mfma_f32_16x16x32_bf16 v[114:117], v[154:157], v[194:197], v[114:117]
	v_mfma_f32_16x16x32_bf16 v[110:113], v[146:149], v[202:205], v[110:113]
	v_mfma_f32_16x16x32_bf16 v[106:109], v[154:157], v[202:205], v[106:109]
	v_mfma_f32_16x16x32_bf16 v[102:105], v[146:149], v[210:213], v[102:105]
	v_mfma_f32_16x16x32_bf16 v[98:101], v[154:157], v[210:213], v[98:101]
	v_mfma_f32_16x16x32_bf16 v[126:129], v[150:153], v[190:193], v[126:129]
	v_mfma_f32_16x16x32_bf16 v[122:125], v[158:161], v[190:193], v[122:125]
	v_mfma_f32_16x16x32_bf16 v[118:121], v[150:153], v[198:201], v[118:121]
	v_mfma_f32_16x16x32_bf16 v[114:117], v[158:161], v[198:201], v[114:117]
	v_mfma_f32_16x16x32_bf16 v[110:113], v[150:153], v[206:209], v[110:113]
	v_mfma_f32_16x16x32_bf16 v[106:109], v[158:161], v[206:209], v[106:109]
	v_mfma_f32_16x16x32_bf16 v[102:105], v[150:153], v[214:217], v[102:105]
	v_mfma_f32_16x16x32_bf16 v[98:101], v[158:161], v[214:217], v[98:101]
	v_mfma_f32_16x16x32_bf16 v[94:97], v[168:171], v[186:189], v[94:97]
	v_mfma_f32_16x16x32_bf16 v[90:93], v[176:179], v[186:189], v[90:93]
	v_mfma_f32_16x16x32_bf16 v[86:89], v[168:171], v[194:197], v[86:89]
	v_mfma_f32_16x16x32_bf16 v[82:85], v[176:179], v[194:197], v[82:85]
	v_mfma_f32_16x16x32_bf16 v[78:81], v[168:171], v[202:205], v[78:81]
	v_mfma_f32_16x16x32_bf16 v[74:77], v[176:179], v[202:205], v[74:77]
	v_mfma_f32_16x16x32_bf16 v[70:73], v[168:171], v[210:213], v[70:73]
	v_mfma_f32_16x16x32_bf16 v[66:69], v[176:179], v[210:213], v[66:69]
	v_mfma_f32_16x16x32_bf16 v[94:97], v[172:175], v[190:193], v[94:97]
	v_mfma_f32_16x16x32_bf16 v[90:93], v[180:183], v[190:193], v[90:93]
	v_mfma_f32_16x16x32_bf16 v[86:89], v[172:175], v[198:201], v[86:89]
	v_mfma_f32_16x16x32_bf16 v[82:85], v[180:183], v[198:201], v[82:85]
	v_mfma_f32_16x16x32_bf16 v[78:81], v[172:175], v[206:209], v[78:81]
	v_mfma_f32_16x16x32_bf16 v[74:77], v[180:183], v[206:209], v[74:77]
	v_mfma_f32_16x16x32_bf16 v[70:73], v[172:175], v[214:217], v[70:73]
	v_mfma_f32_16x16x32_bf16 v[66:69], v[180:183], v[214:217], v[66:69]
	s_setprio 0
	s_barrier
	s_add_i32 s73, s64, s52
	v_lshl_add_u64 v[218:219], s[46:47], 0, v[132:133]
	s_mov_b32 m0, s73
	ds_read_b128 v[186:189], v167 offset:16384
	ds_read_b128 v[190:193], v167 offset:17408
	ds_read_b128 v[194:197], v167 offset:18432
	ds_read_b128 v[198:201], v167 offset:19456
	ds_read_b128 v[202:205], v167 offset:20480
	ds_read_b128 v[206:209], v167 offset:21504
	ds_read_b128 v[210:213], v167 offset:22528
	ds_read_b128 v[214:217], v167 offset:23552
	global_load_lds_dwordx4 v[218:219], off
	s_add_i32 m0, s73, 0x2000
	s_add_u32 s74, s46, 0x20000
	v_lshl_add_u64 v[220:221], s[46:47], 0, v[136:137]
	s_addc_u32 s75, s47, 0
	s_add_i32 s73, s65, s52
	global_load_lds_dwordx4 v[220:221], off
	v_lshl_add_u64 v[222:223], s[74:75], 0, v[132:133]
	s_mov_b32 m0, s73
	v_lshl_add_u64 v[224:225], s[48:49], 0, v[134:135]
	global_load_lds_dwordx4 v[222:223], off
	v_lshl_add_u64 v[222:223], s[74:75], 0, v[136:137]
	s_add_i32 m0, s73, 0x2000
	s_nop 0
	global_load_lds_dwordx4 v[222:223], off
	v_lshl_add_u64 v[222:223], s[48:49], 0, v[130:131]
	s_mov_b32 m0, s53
	s_nop 0
	global_load_lds_dwordx4 v[222:223], off
	s_mov_b32 m0, s54
	s_nop 0
	global_load_lds_dwordx4 v[224:225], off
	s_waitcnt vmcnt(8)
	s_waitcnt lgkmcnt(0)
	s_barrier
; #define PG8_STAGE(bufoff, gbase, voff) do { _Pragma("unroll") for (int _i = 0; _i < 2; ++_i) \
;         __builtin_amdgcn_global_load_lds((const unsigned*)((const char*)(gbase) + (voff)[_i]), (LAS unsigned*)(lds + (bufoff) + ldsw + _i * 8192), 16, 0, 0); } while (0)
; #define PG8_LDA(dst, b, h) do { _Pragma("unroll") for (int m = 0; m < 4; ++m) _Pragma("unroll") for (int k = 0; k < 2; ++k) dst[m][k] = *(const LAS bf16x8*)(lds + PG8_SA(b, h) + aoff + m * 2048 + k * 1024); } while (0)
; #define PG8_LDB(dst, b, h) do { _Pragma("unroll") for (int n = 0; n < 2; ++n) _Pragma("unroll") for (int k = 0; k < 2; ++k) dst[n][k] = *(const LAS bf16x8*)(lds + PG8_SB(b, h) + boff + n * 2048 + k * 1024); } while (0)
; #define PG8_MMA(ai, bj, At, Bt) do { __builtin_amdgcn_s_setprio(1); _Pragma("unroll") for (int m = 0; m < 4; ++m) _Pragma("unroll") for (int n = 0; n < 2; ++n) _Pragma("unroll") for (int k = 0; k < 2; ++k) \
;         acc[ai][bj][m][n] = __builtin_amdgcn_mfma_f32_16x16x32_bf16(Bt[n][k], At[m][k], acc[ai][bj][m][n], 0, 0, 0); __builtin_amdgcn_s_setprio(0); } while (0)
; #define PG8_WAIT_V(n) asm volatile("s_waitcnt vmcnt(" #n ")" ::: "memory")
; #define PG8_WAIT_L(n) asm volatile("s_waitcnt lgkmcnt(" #n ")" ::: "memory")
; #define PG8_BAR __builtin_amdgcn_s_barrier()
; #define PG8_SCHED __builtin_amdgcn_sched_barrier(0)
; template <class Epi, class Sched>
; DI void gemm_phase(LAS unsigned char* lds, const Gemm g, const Sched& S, const Epi& E) {
;     ...
;             PG8_WAIT_V(8); PG8_WAIT_L(0); PG8_BAR; PG8_MMA(1, 0, At, B0); PG8_MMA(1, 1, At, B1); PG8_BAR; PG8_SCHED;
;             PG8_LDB(B0, 1, 0); PG8_LDB(B1, 1, 1); PG8_SCHED; PG8_LDA(At, 1, 0); PG8_STAGE(PG8_SA(0, 1), a2 + hstepA, voffA);
;             PG8_WAIT_V(8); PG8_WAIT_L(0); PG8_BAR; PG8_MMA(0, 0, At, B0); PG8_MMA(0, 1, At, B1); PG8_BAR; PG8_SCHED;
	s_setprio 1
	v_mfma_f32_16x16x32_bf16 v[62:65], v[146:149], v[186:189], v[62:65]
	v_mfma_f32_16x16x32_bf16 v[58:61], v[154:157], v[186:189], v[58:61]
	v_mfma_f32_16x16x32_bf16 v[54:57], v[146:149], v[194:197], v[54:57]
	v_mfma_f32_16x16x32_bf16 v[50:53], v[154:157], v[194:197], v[50:53]
	v_mfma_f32_16x16x32_bf16 v[46:49], v[146:149], v[202:205], v[46:49]
	v_mfma_f32_16x16x32_bf16 v[42:45], v[154:157], v[202:205], v[42:45]
	v_mfma_f32_16x16x32_bf16 v[38:41], v[146:149], v[210:213], v[38:41]
	v_mfma_f32_16x16x32_bf16 v[34:37], v[154:157], v[210:213], v[34:37]
	v_mfma_f32_16x16x32_bf16 v[62:65], v[150:153], v[190:193], v[62:65]
	v_mfma_f32_16x16x32_bf16 v[58:61], v[158:161], v[190:193], v[58:61]
	v_mfma_f32_16x16x32_bf16 v[54:57], v[150:153], v[198:201], v[54:57]
	v_mfma_f32_16x16x32_bf16 v[50:53], v[158:161], v[198:201], v[50:53]
	v_mfma_f32_16x16x32_bf16 v[46:49], v[150:153], v[206:209], v[46:49]
	v_mfma_f32_16x16x32_bf16 v[42:45], v[158:161], v[206:209], v[42:45]
	v_mfma_f32_16x16x32_bf16 v[38:41], v[150:153], v[214:217], v[38:41]
	v_mfma_f32_16x16x32_bf16 v[34:37], v[158:161], v[214:217], v[34:37]
	v_mfma_f32_16x16x32_bf16 v[30:33], v[168:171], v[186:189], v[30:33]
	v_mfma_f32_16x16x32_bf16 v[26:29], v[176:179], v[186:189], v[26:29]
	v_mfma_f32_16x16x32_bf16 v[22:25], v[168:171], v[194:197], v[22:25]
	v_mfma_f32_16x16x32_bf16 v[18:21], v[176:179], v[194:197], v[18:21]
	v_mfma_f32_16x16x32_bf16 v[14:17], v[168:171], v[202:205], v[14:17]
	v_mfma_f32_16x16x32_bf16 v[10:13], v[176:179], v[202:205], v[10:13]
	v_mfma_f32_16x16x32_bf16 v[6:9], v[168:171], v[210:213], v[6:9]
	v_mfma_f32_16x16x32_bf16 v[2:5], v[176:179], v[210:213], v[2:5]
	v_mfma_f32_16x16x32_bf16 v[30:33], v[172:175], v[190:193], v[30:33]
	v_mfma_f32_16x16x32_bf16 v[26:29], v[180:183], v[190:193], v[26:29]
	v_mfma_f32_16x16x32_bf16 v[22:25], v[172:175], v[198:201], v[22:25]
	v_mfma_f32_16x16x32_bf16 v[18:21], v[180:183], v[198:201], v[18:21]
	v_mfma_f32_16x16x32_bf16 v[14:17], v[172:175], v[206:209], v[14:17]
	v_mfma_f32_16x16x32_bf16 v[10:13], v[180:183], v[206:209], v[10:13]
	v_mfma_f32_16x16x32_bf16 v[6:9], v[172:175], v[214:217], v[6:9]
	v_mfma_f32_16x16x32_bf16 v[2:5], v[180:183], v[214:217], v[2:5]
	s_setprio 0
	s_barrier
	s_add_i32 s73, 0, 0x18000
	s_add_i32 s74, 0, 0x1c000
	v_add_u32_e32 v158, s73, v162
	v_add_u32_e32 v180, s74, v162
	ds_read_b128 v[146:149], v158
	ds_read_b128 v[150:153], v158 offset:1024
	ds_read_b128 v[154:157], v158 offset:2048
	ds_read_b128 v[158:161], v158 offset:3072
	ds_read_b128 v[168:171], v180
	ds_read_b128 v[172:175], v180 offset:1024
	ds_read_b128 v[176:179], v180 offset:2048
	ds_read_b128 v[180:183], v180 offset:3072
	s_add_u32 s48, s48, 0x20000
	s_addc_u32 s49, s49, 0
	s_mov_b32 m0, s55
	v_lshl_add_u64 v[226:227], s[48:49], 0, v[130:131]
	ds_read_b128 v[186:189], v167 offset:32768
	ds_read_b128 v[190:193], v167 offset:33792
	ds_read_b128 v[194:197], v167 offset:34816
	ds_read_b128 v[198:201], v167 offset:35840
	ds_read_b128 v[202:205], v167 offset:36864
	ds_read_b128 v[206:209], v167 offset:37888
	ds_read_b128 v[210:213], v167 offset:38912
	ds_read_b128 v[214:217], v167 offset:39936
	global_load_lds_dwordx4 v[226:227], off
	v_lshl_add_u64 v[226:227], s[48:49], 0, v[134:135]
	s_mov_b32 m0, s56
	s_nop 0
	global_load_lds_dwordx4 v[226:227], off
	s_waitcnt vmcnt(8)
	s_waitcnt lgkmcnt(0)
	s_barrier
	s_setprio 1
	v_mfma_f32_16x16x32_bf16 v[126:129], v[146:149], v[186:189], v[126:129]
	v_mfma_f32_16x16x32_bf16 v[122:125], v[154:157], v[186:189], v[122:125]
	v_mfma_f32_16x16x32_bf16 v[118:121], v[146:149], v[194:197], v[118:121]
	v_mfma_f32_16x16x32_bf16 v[114:117], v[154:157], v[194:197], v[114:117]
	v_mfma_f32_16x16x32_bf16 v[110:113], v[146:149], v[202:205], v[110:113]
	v_mfma_f32_16x16x32_bf16 v[106:109], v[154:157], v[202:205], v[106:109]
	v_mfma_f32_16x16x32_bf16 v[102:105], v[146:149], v[210:213], v[102:105]
	v_mfma_f32_16x16x32_bf16 v[98:101], v[154:157], v[210:213], v[98:101]
	v_mfma_f32_16x16x32_bf16 v[126:129], v[150:153], v[190:193], v[126:129]
	v_mfma_f32_16x16x32_bf16 v[122:125], v[158:161], v[190:193], v[122:125]
	v_mfma_f32_16x16x32_bf16 v[118:121], v[150:153], v[198:201], v[118:121]
	v_mfma_f32_16x16x32_bf16 v[114:117], v[158:161], v[198:201], v[114:117]
	v_mfma_f32_16x16x32_bf16 v[110:113], v[150:153], v[206:209], v[110:113]
	v_mfma_f32_16x16x32_bf16 v[106:109], v[158:161], v[206:209], v[106:109]
	v_mfma_f32_16x16x32_bf16 v[102:105], v[150:153], v[214:217], v[102:105]
	v_mfma_f32_16x16x32_bf16 v[98:101], v[158:161], v[214:217], v[98:101]
	v_mfma_f32_16x16x32_bf16 v[94:97], v[168:171], v[186:189], v[94:97]
	v_mfma_f32_16x16x32_bf16 v[90:93], v[176:179], v[186:189], v[90:93]
	v_mfma_f32_16x16x32_bf16 v[86:89], v[168:171], v[194:197], v[86:89]
	v_mfma_f32_16x16x32_bf16 v[82:85], v[176:179], v[194:197], v[82:85]
	v_mfma_f32_16x16x32_bf16 v[78:81], v[168:171], v[202:205], v[78:81]
	v_mfma_f32_16x16x32_bf16 v[74:77], v[176:179], v[202:205], v[74:77]
	v_mfma_f32_16x16x32_bf16 v[70:73], v[168:171], v[210:213], v[70:73]
	v_mfma_f32_16x16x32_bf16 v[66:69], v[176:179], v[210:213], v[66:69]
	v_mfma_f32_16x16x32_bf16 v[94:97], v[172:175], v[190:193], v[94:97]
	v_mfma_f32_16x16x32_bf16 v[90:93], v[180:183], v[190:193], v[90:93]
	v_mfma_f32_16x16x32_bf16 v[86:89], v[172:175], v[198:201], v[86:89]
	v_mfma_f32_16x16x32_bf16 v[82:85], v[180:183], v[198:201], v[82:85]
	v_mfma_f32_16x16x32_bf16 v[78:81], v[172:175], v[206:209], v[78:81]
	v_mfma_f32_16x16x32_bf16 v[74:77], v[180:183], v[206:209], v[74:77]
	v_mfma_f32_16x16x32_bf16 v[70:73], v[172:175], v[214:217], v[70:73]
	v_mfma_f32_16x16x32_bf16 v[66:69], v[180:183], v[214:217], v[66:69]
	s_setprio 0
	s_barrier
; #define PG8_STAGE(bufoff, gbase, voff) do { _Pragma("unroll") for (int _i = 0; _i < 2; ++_i) \
;         __builtin_amdgcn_global_load_lds((const unsigned*)((const char*)(gbase) + (voff)[_i]), (LAS unsigned*)(lds + (bufoff) + ldsw + _i * 8192), 16, 0, 0); } while (0)
; #define PG8_LDA(dst, b, h) do { _Pragma("unroll") for (int m = 0; m < 4; ++m) _Pragma("unroll") for (int k = 0; k < 2; ++k) dst[m][k] = *(const LAS bf16x8*)(lds + PG8_SA(b, h) + aoff + m * 2048 + k * 1024); } while (0)
; #define PG8_MMA(ai, bj, At, Bt) do { __builtin_amdgcn_s_setprio(1); _Pragma("unroll") for (int m = 0; m < 4; ++m) _Pragma("unroll") for (int n = 0; n < 2; ++n) _Pragma("unroll") for (int k = 0; k < 2; ++k) \
;         acc[ai][bj][m][n] = __builtin_amdgcn_mfma_f32_16x16x32_bf16(Bt[n][k], At[m][k], acc[ai][bj][m][n], 0, 0, 0); __builtin_amdgcn_s_setprio(0); } while (0)
; #define PG8_WAIT_V(n) asm volatile("s_waitcnt vmcnt(" #n ")" ::: "memory")
; #define PG8_WAIT_L(n) asm volatile("s_waitcnt lgkmcnt(" #n ")" ::: "memory")
; #define PG8_BAR __builtin_amdgcn_s_barrier()
; #define PG8_SCHED __builtin_amdgcn_sched_barrier(0)
;     DI void pre(Pre& pr, const pg8::Unit& u, int wr, int fr) const { load_rows(pr, ssq, u, wr, fr); }
;     DI void pre(Pre& pr, const pg8::Unit& u, int wr, int fr) const { load_rows(pr, ssq, u, wr, fr); }
; template <class Epi, class Sched>
; DI void gemm_phase(LAS unsigned char* lds, const Gemm g, const Sched& S, const Epi& E) {
;     ...
;             PG8_LDA(At, 1, 1); PG8_STAGE(PG8_SB(1, 0), b3, voffB); PG8_STAGE(PG8_SB(1, 1), b3 + hstepB, voffB); PG8_STAGE(PG8_SA(1, 0), a3, voffA);
;             PG8_WAIT_V(8); PG8_WAIT_L(0); PG8_BAR; PG8_MMA(1, 0, At, B0); PG8_MMA(1, 1, At, B1); PG8_BAR; PG8_SCHED;
;         }
;         if (wr == 0) PG8_BAR;
;         E(acc, cur, wr, wc, fr, fq, pre);
	s_add_i32 s48, s73, s52
	v_lshl_add_u64 v[218:219], v[218:219], 0, s[20:21]
	s_mov_b32 m0, s48
	ds_read_b128 v[186:189], v167 offset:49152
	ds_read_b128 v[190:193], v167 offset:50176
	ds_read_b128 v[194:197], v167 offset:51200
	ds_read_b128 v[198:201], v167 offset:52224
	ds_read_b128 v[202:205], v167 offset:53248
	ds_read_b128 v[206:209], v167 offset:54272
	ds_read_b128 v[210:213], v167 offset:55296
	ds_read_b128 v[214:217], v167 offset:56320
	global_load_lds_dwordx4 v[218:219], off
	s_add_i32 m0, s48, 0x2000
	s_add_u32 s46, s46, 0x20080
	v_lshl_add_u64 v[218:219], v[220:221], 0, s[20:21]
	s_addc_u32 s47, s47, 0
	s_add_i32 s48, s74, s52
	global_load_lds_dwordx4 v[218:219], off
	v_lshl_add_u64 v[218:219], s[46:47], 0, v[132:133]
	s_mov_b32 m0, s48
	s_nop 0
	global_load_lds_dwordx4 v[218:219], off
	v_lshl_add_u64 v[218:219], s[46:47], 0, v[136:137]
	s_add_i32 m0, s48, 0x2000
	s_nop 0
	global_load_lds_dwordx4 v[218:219], off
	v_lshl_add_u64 v[218:219], v[222:223], 0, s[20:21]
	s_mov_b32 m0, s61
	s_nop 0
	global_load_lds_dwordx4 v[218:219], off
	v_lshl_add_u64 v[218:219], v[224:225], 0, s[20:21]
	s_mov_b32 m0, s62
	s_nop 0
	global_load_lds_dwordx4 v[218:219], off
	s_waitcnt vmcnt(8)
	s_waitcnt lgkmcnt(0)
	s_barrier
	s_setprio 1
	v_mfma_f32_16x16x32_bf16 v[62:65], v[146:149], v[186:189], v[62:65]
	v_mfma_f32_16x16x32_bf16 v[58:61], v[154:157], v[186:189], v[58:61]
	v_mfma_f32_16x16x32_bf16 v[54:57], v[146:149], v[194:197], v[54:57]
	v_mfma_f32_16x16x32_bf16 v[50:53], v[154:157], v[194:197], v[50:53]
	v_mfma_f32_16x16x32_bf16 v[46:49], v[146:149], v[202:205], v[46:49]
	v_mfma_f32_16x16x32_bf16 v[42:45], v[154:157], v[202:205], v[42:45]
	v_mfma_f32_16x16x32_bf16 v[38:41], v[146:149], v[210:213], v[38:41]
	v_mfma_f32_16x16x32_bf16 v[34:37], v[154:157], v[210:213], v[34:37]
	v_mfma_f32_16x16x32_bf16 v[62:65], v[150:153], v[190:193], v[62:65]
	v_mfma_f32_16x16x32_bf16 v[58:61], v[158:161], v[190:193], v[58:61]
	v_mfma_f32_16x16x32_bf16 v[54:57], v[150:153], v[198:201], v[54:57]
	v_mfma_f32_16x16x32_bf16 v[50:53], v[158:161], v[198:201], v[50:53]
	v_mfma_f32_16x16x32_bf16 v[46:49], v[150:153], v[206:209], v[46:49]
	v_mfma_f32_16x16x32_bf16 v[42:45], v[158:161], v[206:209], v[42:45]
	v_mfma_f32_16x16x32_bf16 v[38:41], v[150:153], v[214:217], v[38:41]
	v_mfma_f32_16x16x32_bf16 v[34:37], v[158:161], v[214:217], v[34:37]
	v_mfma_f32_16x16x32_bf16 v[30:33], v[168:171], v[186:189], v[30:33]
	v_mfma_f32_16x16x32_bf16 v[26:29], v[176:179], v[186:189], v[26:29]
	v_mfma_f32_16x16x32_bf16 v[22:25], v[168:171], v[194:197], v[22:25]
	v_mfma_f32_16x16x32_bf16 v[18:21], v[176:179], v[194:197], v[18:21]
	v_mfma_f32_16x16x32_bf16 v[14:17], v[168:171], v[202:205], v[14:17]
	v_mfma_f32_16x16x32_bf16 v[10:13], v[176:179], v[202:205], v[10:13]
	v_mfma_f32_16x16x32_bf16 v[6:9], v[168:171], v[210:213], v[6:9]
	v_mfma_f32_16x16x32_bf16 v[2:5], v[176:179], v[210:213], v[2:5]
	v_mfma_f32_16x16x32_bf16 v[30:33], v[172:175], v[190:193], v[30:33]
	v_mfma_f32_16x16x32_bf16 v[26:29], v[180:183], v[190:193], v[26:29]
	v_mfma_f32_16x16x32_bf16 v[22:25], v[172:175], v[198:201], v[22:25]
	v_mfma_f32_16x16x32_bf16 v[18:21], v[180:183], v[198:201], v[18:21]
	v_mfma_f32_16x16x32_bf16 v[14:17], v[172:175], v[206:209], v[14:17]
	v_mfma_f32_16x16x32_bf16 v[10:13], v[180:183], v[206:209], v[10:13]
	v_mfma_f32_16x16x32_bf16 v[6:9], v[172:175], v[214:217], v[6:9]
	v_mfma_f32_16x16x32_bf16 v[2:5], v[180:183], v[214:217], v[2:5]
	s_setprio 0
	s_barrier
	s_add_i32 s72, s72, 2
	s_add_u32 s44, s44, 0x100
	s_addc_u32 s45, s45, 0
	s_add_u32 s70, s70, 0x100
	s_addc_u32 s71, s71, 0
	s_cmp_gt_u32 s72, 5
	s_cbranch_scc0 .LBB0_972
	s_mov_b32 s99, 1
	s_and_b64 vcc, exec, s[34:35]
	s_cbranch_vccz .LBB0_975
	s_barrier

; #define PG8_STAGE(bufoff, gbase, voff) do { _Pragma("unroll") for (int _i = 0; _i < 2; ++_i) \
;         __builtin_amdgcn_global_load_lds((const unsigned*)((const char*)(gbase) + (voff)[_i]), (LAS unsigned*)(lds + (bufoff) + ldsw + _i * 8192), 16, 0, 0); } while (0)
; #define PG8_LDA(dst, b, h) do { _Pragma("unroll") for (int m = 0; m < 4; ++m) _Pragma("unroll") for (int k = 0; k < 2; ++k) dst[m][k] = *(const LAS bf16x8*)(lds + PG8_SA(b, h) + aoff + m * 2048 + k * 1024); } while (0)
; #define PG8_LDB(dst, b, h) do { _Pragma("unroll") for (int n = 0; n < 2; ++n) _Pragma("unroll") for (int k = 0; k < 2; ++k) dst[n][k] = *(const LAS bf16x8*)(lds + PG8_SB(b, h) + boff + n * 2048 + k * 1024); } while (0)
; #define PG8_MMA(ai, bj, At, Bt) do { __builtin_amdgcn_s_setprio(1); _Pragma("unroll") for (int m = 0; m < 4; ++m) _Pragma("unroll") for (int n = 0; n < 2; ++n) _Pragma("unroll") for (int k = 0; k < 2; ++k) \
;         acc[ai][bj][m][n] = __builtin_amdgcn_mfma_f32_16x16x32_bf16(Bt[n][k], At[m][k], acc[ai][bj][m][n], 0, 0, 0); __builtin_amdgcn_s_setprio(0); } while (0)
; #define PG8_WAIT_V(n) asm volatile("s_waitcnt vmcnt(" #n ")" ::: "memory")
; #define PG8_WAIT_L(n) asm volatile("s_waitcnt lgkmcnt(" #n ")" ::: "memory")
; #define PG8_BAR __builtin_amdgcn_s_barrier()
; #define PG8_SCHED __builtin_amdgcn_sched_barrier(0)
; template <class Epi, class Sched>
; DI void gemm_phase(LAS unsigned char* lds, const Gemm g, const Sched& S, const Epi& E) {
;     ...
;             PG8_LDB(B0, 0, 0); PG8_LDB(B1, 0, 1); PG8_SCHED; PG8_LDA(At, 0, 0); PG8_STAGE(PG8_SA(1, 1), a1 + hstepA, voffA);
;             PG8_WAIT_V(8); PG8_WAIT_L(0); PG8_BAR; PG8_MMA(0, 0, At, B0); PG8_MMA(0, 1, At, B1); PG8_BAR; PG8_SCHED;
;             PG8_LDA(At, 0, 1); PG8_STAGE(PG8_SB(0, 0), b2, voffB); PG8_STAGE(PG8_SB(0, 1), b2 + hstepB, voffB); PG8_STAGE(PG8_SA(0, 0), a2, voffA);
;             PG8_WAIT_V(8); PG8_WAIT_L(0); PG8_BAR; PG8_MMA(1, 0, At, B0); PG8_MMA(1, 1, At, B1); PG8_BAR; PG8_SCHED;
.LBB0_1133:
	ds_read_b128 v[146:149], v152
	ds_read_b128 v[156:159], v152 offset:1024
	ds_read_b128 v[160:163], v152 offset:2048
	ds_read_b128 v[164:167], v152 offset:3072
	ds_read_b128 v[168:171], v153
	ds_read_b128 v[172:175], v153 offset:1024
	ds_read_b128 v[176:179], v153 offset:2048
	ds_read_b128 v[180:183], v153 offset:3072
	s_add_u32 s46, s44, 0xfffc0080
	s_addc_u32 s47, s45, -1
	s_cmp_eq_u32 s66, 12
	s_cselect_b32 s49, s35, s47
	s_cselect_b32 s48, s41, s46
	s_cselect_b32 s47, s21, s65
	s_cselect_b32 s46, s63, s64
	v_lshl_add_u64 v[218:219], s[44:45], 0, v[138:139]
	s_add_i32 m0, s43, 0xc000
	ds_read_b128 v[186:189], v154
	ds_read_b128 v[190:193], v154 offset:1024
	ds_read_b128 v[194:197], v154 offset:2048
	ds_read_b128 v[198:201], v154 offset:3072
	ds_read_b128 v[202:205], v154 offset:4096
	ds_read_b128 v[206:209], v154 offset:5120
	ds_read_b128 v[210:213], v154 offset:6144
	ds_read_b128 v[214:217], v154 offset:7168
	global_load_lds_dwordx4 v[218:219], off
	v_lshl_add_u64 v[218:219], s[44:45], 0, v[140:141]
	s_add_i32 m0, s43, 0xe000
	s_nop 0
	global_load_lds_dwordx4 v[218:219], off
	s_waitcnt vmcnt(8)
	s_waitcnt lgkmcnt(0)
	s_barrier
	s_setprio 1
	v_mfma_f32_16x16x32_bf16 v[126:129], v[146:149], v[186:189], v[126:129]
	v_mfma_f32_16x16x32_bf16 v[122:125], v[160:163], v[186:189], v[122:125]
	v_mfma_f32_16x16x32_bf16 v[110:113], v[146:149], v[194:197], v[110:113]
	v_mfma_f32_16x16x32_bf16 v[106:109], v[160:163], v[194:197], v[106:109]
	v_mfma_f32_16x16x32_bf16 v[94:97], v[146:149], v[202:205], v[94:97]
	v_mfma_f32_16x16x32_bf16 v[90:93], v[160:163], v[202:205], v[90:93]
	v_mfma_f32_16x16x32_bf16 v[78:81], v[146:149], v[210:213], v[78:81]
	v_mfma_f32_16x16x32_bf16 v[74:77], v[160:163], v[210:213], v[74:77]
	v_mfma_f32_16x16x32_bf16 v[126:129], v[156:159], v[190:193], v[126:129]
	v_mfma_f32_16x16x32_bf16 v[122:125], v[164:167], v[190:193], v[122:125]
	v_mfma_f32_16x16x32_bf16 v[110:113], v[156:159], v[198:201], v[110:113]
	v_mfma_f32_16x16x32_bf16 v[106:109], v[164:167], v[198:201], v[106:109]
	v_mfma_f32_16x16x32_bf16 v[94:97], v[156:159], v[206:209], v[94:97]
	v_mfma_f32_16x16x32_bf16 v[90:93], v[164:167], v[206:209], v[90:93]
	v_mfma_f32_16x16x32_bf16 v[78:81], v[156:159], v[214:217], v[78:81]
	v_mfma_f32_16x16x32_bf16 v[74:77], v[164:167], v[214:217], v[74:77]
	v_mfma_f32_16x16x32_bf16 v[118:121], v[168:171], v[186:189], v[118:121]
	v_mfma_f32_16x16x32_bf16 v[114:117], v[176:179], v[186:189], v[114:117]
	v_mfma_f32_16x16x32_bf16 v[102:105], v[168:171], v[194:197], v[102:105]
	v_mfma_f32_16x16x32_bf16 v[98:101], v[176:179], v[194:197], v[98:101]
	v_mfma_f32_16x16x32_bf16 v[86:89], v[168:171], v[202:205], v[86:89]
	v_mfma_f32_16x16x32_bf16 v[82:85], v[176:179], v[202:205], v[82:85]
	v_mfma_f32_16x16x32_bf16 v[70:73], v[168:171], v[210:213], v[70:73]
	v_mfma_f32_16x16x32_bf16 v[66:69], v[176:179], v[210:213], v[66:69]
	v_mfma_f32_16x16x32_bf16 v[118:121], v[172:175], v[190:193], v[118:121]
	v_mfma_f32_16x16x32_bf16 v[114:117], v[180:183], v[190:193], v[114:117]
	v_mfma_f32_16x16x32_bf16 v[102:105], v[172:175], v[198:201], v[102:105]
	v_mfma_f32_16x16x32_bf16 v[98:101], v[180:183], v[198:201], v[98:101]
	v_mfma_f32_16x16x32_bf16 v[86:89], v[172:175], v[206:209], v[86:89]
	v_mfma_f32_16x16x32_bf16 v[82:85], v[180:183], v[206:209], v[82:85]
	v_mfma_f32_16x16x32_bf16 v[70:73], v[172:175], v[214:217], v[70:73]
	v_mfma_f32_16x16x32_bf16 v[66:69], v[180:183], v[214:217], v[66:69]
	s_setprio 0
	s_barrier
	s_add_i32 s67, s61, s52
	v_lshl_add_u64 v[218:219], s[46:47], 0, v[132:133]
	s_mov_b32 m0, s67
	ds_read_b128 v[186:189], v154 offset:16384
	ds_read_b128 v[190:193], v154 offset:17408
	ds_read_b128 v[194:197], v154 offset:18432
	ds_read_b128 v[198:201], v154 offset:19456
	ds_read_b128 v[202:205], v154 offset:20480
	ds_read_b128 v[206:209], v154 offset:21504
	ds_read_b128 v[210:213], v154 offset:22528
	ds_read_b128 v[214:217], v154 offset:23552
	global_load_lds_dwordx4 v[218:219], off
	s_add_i32 m0, s67, 0x2000
	s_add_u32 s68, s46, 0x40000
	v_lshl_add_u64 v[220:221], s[46:47], 0, v[136:137]
	s_addc_u32 s69, s47, 0
	s_add_i32 s67, s62, s52
	global_load_lds_dwordx4 v[220:221], off
	v_lshl_add_u64 v[222:223], s[68:69], 0, v[132:133]
	s_mov_b32 m0, s67
	v_lshl_add_u64 v[224:225], s[48:49], 0, v[134:135]
	global_load_lds_dwordx4 v[222:223], off
	v_lshl_add_u64 v[222:223], s[68:69], 0, v[136:137]
	s_add_i32 m0, s67, 0x2000
	s_nop 0
	global_load_lds_dwordx4 v[222:223], off
	v_lshl_add_u64 v[222:223], s[48:49], 0, v[130:131]
	s_mov_b32 m0, s43
	s_nop 0
	global_load_lds_dwordx4 v[222:223], off
	s_mov_b32 m0, s53
	s_nop 0
	global_load_lds_dwordx4 v[224:225], off
	s_waitcnt vmcnt(8)
	s_waitcnt lgkmcnt(0)
	s_barrier
; #define PG8_STAGE(bufoff, gbase, voff) do { _Pragma("unroll") for (int _i = 0; _i < 2; ++_i) \
;         __builtin_amdgcn_global_load_lds((const unsigned*)((const char*)(gbase) + (voff)[_i]), (LAS unsigned*)(lds + (bufoff) + ldsw + _i * 8192), 16, 0, 0); } while (0)
; #define PG8_LDA(dst, b, h) do { _Pragma("unroll") for (int m = 0; m < 4; ++m) _Pragma("unroll") for (int k = 0; k < 2; ++k) dst[m][k] = *(const LAS bf16x8*)(lds + PG8_SA(b, h) + aoff + m * 2048 + k * 1024); } while (0)
; #define PG8_LDB(dst, b, h) do { _Pragma("unroll") for (int n = 0; n < 2; ++n) _Pragma("unroll") for (int k = 0; k < 2; ++k) dst[n][k] = *(const LAS bf16x8*)(lds + PG8_SB(b, h) + boff + n * 2048 + k * 1024); } while (0)
; #define PG8_MMA(ai, bj, At, Bt) do { __builtin_amdgcn_s_setprio(1); _Pragma("unroll") for (int m = 0; m < 4; ++m) _Pragma("unroll") for (int n = 0; n < 2; ++n) _Pragma("unroll") for (int k = 0; k < 2; ++k) \
;         acc[ai][bj][m][n] = __builtin_amdgcn_mfma_f32_16x16x32_bf16(Bt[n][k], At[m][k], acc[ai][bj][m][n], 0, 0, 0); __builtin_amdgcn_s_setprio(0); } while (0)
; #define PG8_WAIT_V(n) asm volatile("s_waitcnt vmcnt(" #n ")" ::: "memory")
; #define PG8_WAIT_L(n) asm volatile("s_waitcnt lgkmcnt(" #n ")" ::: "memory")
; #define PG8_BAR __builtin_amdgcn_s_barrier()
; #define PG8_SCHED __builtin_amdgcn_sched_barrier(0)
; template <class Epi, class Sched>
; DI void gemm_phase(LAS unsigned char* lds, const Gemm g, const Sched& S, const Epi& E) {
;     ...
;             PG8_WAIT_V(8); PG8_WAIT_L(0); PG8_BAR; PG8_MMA(1, 0, At, B0); PG8_MMA(1, 1, At, B1); PG8_BAR; PG8_SCHED;
;             PG8_LDB(B0, 1, 0); PG8_LDB(B1, 1, 1); PG8_SCHED; PG8_LDA(At, 1, 0); PG8_STAGE(PG8_SA(0, 1), a2 + hstepA, voffA);
;             PG8_WAIT_V(8); PG8_WAIT_L(0); PG8_BAR; PG8_MMA(0, 0, At, B0); PG8_MMA(0, 1, At, B1); PG8_BAR; PG8_SCHED;
	s_setprio 1
	v_mfma_f32_16x16x32_bf16 v[62:65], v[146:149], v[186:189], v[62:65]
	v_mfma_f32_16x16x32_bf16 v[58:61], v[160:163], v[186:189], v[58:61]
	v_mfma_f32_16x16x32_bf16 v[46:49], v[146:149], v[194:197], v[46:49]
	v_mfma_f32_16x16x32_bf16 v[42:45], v[160:163], v[194:197], v[42:45]
	v_mfma_f32_16x16x32_bf16 v[30:33], v[146:149], v[202:205], v[30:33]
	v_mfma_f32_16x16x32_bf16 v[26:29], v[160:163], v[202:205], v[26:29]
	v_mfma_f32_16x16x32_bf16 v[14:17], v[146:149], v[210:213], v[14:17]
	v_mfma_f32_16x16x32_bf16 v[10:13], v[160:163], v[210:213], v[10:13]
	v_mfma_f32_16x16x32_bf16 v[62:65], v[156:159], v[190:193], v[62:65]
	v_mfma_f32_16x16x32_bf16 v[58:61], v[164:167], v[190:193], v[58:61]
	v_mfma_f32_16x16x32_bf16 v[46:49], v[156:159], v[198:201], v[46:49]
	v_mfma_f32_16x16x32_bf16 v[42:45], v[164:167], v[198:201], v[42:45]
	v_mfma_f32_16x16x32_bf16 v[30:33], v[156:159], v[206:209], v[30:33]
	v_mfma_f32_16x16x32_bf16 v[26:29], v[164:167], v[206:209], v[26:29]
	v_mfma_f32_16x16x32_bf16 v[14:17], v[156:159], v[214:217], v[14:17]
	v_mfma_f32_16x16x32_bf16 v[10:13], v[164:167], v[214:217], v[10:13]
	v_mfma_f32_16x16x32_bf16 v[54:57], v[168:171], v[186:189], v[54:57]
	v_mfma_f32_16x16x32_bf16 v[50:53], v[176:179], v[186:189], v[50:53]
	v_mfma_f32_16x16x32_bf16 v[38:41], v[168:171], v[194:197], v[38:41]
	v_mfma_f32_16x16x32_bf16 v[34:37], v[176:179], v[194:197], v[34:37]
	v_mfma_f32_16x16x32_bf16 v[22:25], v[168:171], v[202:205], v[22:25]
	v_mfma_f32_16x16x32_bf16 v[18:21], v[176:179], v[202:205], v[18:21]
	v_mfma_f32_16x16x32_bf16 v[6:9], v[168:171], v[210:213], v[6:9]
	v_mfma_f32_16x16x32_bf16 v[2:5], v[176:179], v[210:213], v[2:5]
	v_mfma_f32_16x16x32_bf16 v[54:57], v[172:175], v[190:193], v[54:57]
	v_mfma_f32_16x16x32_bf16 v[50:53], v[180:183], v[190:193], v[50:53]
	v_mfma_f32_16x16x32_bf16 v[38:41], v[172:175], v[198:201], v[38:41]
	v_mfma_f32_16x16x32_bf16 v[34:37], v[180:183], v[198:201], v[34:37]
	v_mfma_f32_16x16x32_bf16 v[22:25], v[172:175], v[206:209], v[22:25]
	v_mfma_f32_16x16x32_bf16 v[18:21], v[180:183], v[206:209], v[18:21]
	v_mfma_f32_16x16x32_bf16 v[6:9], v[172:175], v[214:217], v[6:9]
	v_mfma_f32_16x16x32_bf16 v[2:5], v[180:183], v[214:217], v[2:5]
	s_setprio 0
	s_barrier
	s_add_i32 s67, 0, 0x18000
	s_add_i32 s68, 0, 0x1c000
	v_add_u32_e32 v164, s67, v150
	v_add_u32_e32 v180, s68, v150
	ds_read_b128 v[146:149], v164
	ds_read_b128 v[156:159], v164 offset:1024
	ds_read_b128 v[160:163], v164 offset:2048
	ds_read_b128 v[164:167], v164 offset:3072
	ds_read_b128 v[168:171], v180
	ds_read_b128 v[172:175], v180 offset:1024
	ds_read_b128 v[176:179], v180 offset:2048
	ds_read_b128 v[180:183], v180 offset:3072
	s_add_u32 s48, s48, 0x40000
	s_addc_u32 s49, s49, 0
	s_mov_b32 m0, s54
	v_lshl_add_u64 v[226:227], s[48:49], 0, v[130:131]
	ds_read_b128 v[186:189], v154 offset:32768
	ds_read_b128 v[190:193], v154 offset:33792
	ds_read_b128 v[194:197], v154 offset:34816
	ds_read_b128 v[198:201], v154 offset:35840
	ds_read_b128 v[202:205], v154 offset:36864
	ds_read_b128 v[206:209], v154 offset:37888
	ds_read_b128 v[210:213], v154 offset:38912
	ds_read_b128 v[214:217], v154 offset:39936
	global_load_lds_dwordx4 v[226:227], off
	v_lshl_add_u64 v[226:227], s[48:49], 0, v[134:135]
	s_mov_b32 m0, s55
	s_nop 0
	global_load_lds_dwordx4 v[226:227], off
	s_waitcnt vmcnt(8)
	s_waitcnt lgkmcnt(0)
	s_barrier
	s_setprio 1
	v_mfma_f32_16x16x32_bf16 v[126:129], v[146:149], v[186:189], v[126:129]
	v_mfma_f32_16x16x32_bf16 v[122:125], v[160:163], v[186:189], v[122:125]
	v_mfma_f32_16x16x32_bf16 v[110:113], v[146:149], v[194:197], v[110:113]
	v_mfma_f32_16x16x32_bf16 v[106:109], v[160:163], v[194:197], v[106:109]
	v_mfma_f32_16x16x32_bf16 v[94:97], v[146:149], v[202:205], v[94:97]
	v_mfma_f32_16x16x32_bf16 v[90:93], v[160:163], v[202:205], v[90:93]
	v_mfma_f32_16x16x32_bf16 v[78:81], v[146:149], v[210:213], v[78:81]
	v_mfma_f32_16x16x32_bf16 v[74:77], v[160:163], v[210:213], v[74:77]
	v_mfma_f32_16x16x32_bf16 v[126:129], v[156:159], v[190:193], v[126:129]
	v_mfma_f32_16x16x32_bf16 v[122:125], v[164:167], v[190:193], v[122:125]
	v_mfma_f32_16x16x32_bf16 v[110:113], v[156:159], v[198:201], v[110:113]
	v_mfma_f32_16x16x32_bf16 v[106:109], v[164:167], v[198:201], v[106:109]
	v_mfma_f32_16x16x32_bf16 v[94:97], v[156:159], v[206:209], v[94:97]
	v_mfma_f32_16x16x32_bf16 v[90:93], v[164:167], v[206:209], v[90:93]
	v_mfma_f32_16x16x32_bf16 v[78:81], v[156:159], v[214:217], v[78:81]
	v_mfma_f32_16x16x32_bf16 v[74:77], v[164:167], v[214:217], v[74:77]
	v_mfma_f32_16x16x32_bf16 v[118:121], v[168:171], v[186:189], v[118:121]
	v_mfma_f32_16x16x32_bf16 v[114:117], v[176:179], v[186:189], v[114:117]
	v_mfma_f32_16x16x32_bf16 v[102:105], v[168:171], v[194:197], v[102:105]
	v_mfma_f32_16x16x32_bf16 v[98:101], v[176:179], v[194:197], v[98:101]
	v_mfma_f32_16x16x32_bf16 v[86:89], v[168:171], v[202:205], v[86:89]
	v_mfma_f32_16x16x32_bf16 v[82:85], v[176:179], v[202:205], v[82:85]
	v_mfma_f32_16x16x32_bf16 v[70:73], v[168:171], v[210:213], v[70:73]
	v_mfma_f32_16x16x32_bf16 v[66:69], v[176:179], v[210:213], v[66:69]
	v_mfma_f32_16x16x32_bf16 v[118:121], v[172:175], v[190:193], v[118:121]
	v_mfma_f32_16x16x32_bf16 v[114:117], v[180:183], v[190:193], v[114:117]
	v_mfma_f32_16x16x32_bf16 v[102:105], v[172:175], v[198:201], v[102:105]
	v_mfma_f32_16x16x32_bf16 v[98:101], v[180:183], v[198:201], v[98:101]
	v_mfma_f32_16x16x32_bf16 v[86:89], v[172:175], v[206:209], v[86:89]
	v_mfma_f32_16x16x32_bf16 v[82:85], v[180:183], v[206:209], v[82:85]
	v_mfma_f32_16x16x32_bf16 v[70:73], v[172:175], v[214:217], v[70:73]
	v_mfma_f32_16x16x32_bf16 v[66:69], v[180:183], v[214:217], v[66:69]
	s_setprio 0
	s_barrier
; #define PG8_STAGE(bufoff, gbase, voff) do { _Pragma("unroll") for (int _i = 0; _i < 2; ++_i) \
;         __builtin_amdgcn_global_load_lds((const unsigned*)((const char*)(gbase) + (voff)[_i]), (LAS unsigned*)(lds + (bufoff) + ldsw + _i * 8192), 16, 0, 0); } while (0)
; #define PG8_LDA(dst, b, h) do { _Pragma("unroll") for (int m = 0; m < 4; ++m) _Pragma("unroll") for (int k = 0; k < 2; ++k) dst[m][k] = *(const LAS bf16x8*)(lds + PG8_SA(b, h) + aoff + m * 2048 + k * 1024); } while (0)
; #define PG8_MMA(ai, bj, At, Bt) do { __builtin_amdgcn_s_setprio(1); _Pragma("unroll") for (int m = 0; m < 4; ++m) _Pragma("unroll") for (int n = 0; n < 2; ++n) _Pragma("unroll") for (int k = 0; k < 2; ++k) \
;         acc[ai][bj][m][n] = __builtin_amdgcn_mfma_f32_16x16x32_bf16(Bt[n][k], At[m][k], acc[ai][bj][m][n], 0, 0, 0); __builtin_amdgcn_s_setprio(0); } while (0)
; #define PG8_WAIT_V(n) asm volatile("s_waitcnt vmcnt(" #n ")" ::: "memory")
; #define PG8_WAIT_L(n) asm volatile("s_waitcnt lgkmcnt(" #n ")" ::: "memory")
; #define PG8_BAR __builtin_amdgcn_s_barrier()
; #define PG8_SCHED __builtin_amdgcn_sched_barrier(0)
;     DI void pre(Pre& pr, const pg8::Unit& u, int wr, int fr) const { load_rows(pr, ssq, u, wr, fr); }
;     DI void pre(Pre& pr, const pg8::Unit& u, int wr, int fr) const { load_rows(pr, ssq, u, wr, fr); }
; template <class Epi, class Sched>
; DI void gemm_phase(LAS unsigned char* lds, const Gemm g, const Sched& S, const Epi& E) {
;     ...
;             PG8_LDA(At, 1, 1); PG8_STAGE(PG8_SB(1, 0), b3, voffB); PG8_STAGE(PG8_SB(1, 1), b3 + hstepB, voffB); PG8_STAGE(PG8_SA(1, 0), a3, voffA);
;             PG8_WAIT_V(8); PG8_WAIT_L(0); PG8_BAR; PG8_MMA(1, 0, At, B0); PG8_MMA(1, 1, At, B1); PG8_BAR; PG8_SCHED;
;         }
;         if (wr == 0) PG8_BAR;
;         E(acc, cur, wr, wc, fr, fq, pre);
	s_add_i32 s48, s67, s52
	v_lshl_add_u64 v[218:219], v[218:219], 0, s[16:17]
	s_mov_b32 m0, s48
	ds_read_b128 v[186:189], v154 offset:49152
	ds_read_b128 v[190:193], v154 offset:50176
	ds_read_b128 v[194:197], v154 offset:51200
	ds_read_b128 v[198:201], v154 offset:52224
	ds_read_b128 v[202:205], v154 offset:53248
	ds_read_b128 v[206:209], v154 offset:54272
	ds_read_b128 v[210:213], v154 offset:55296
	ds_read_b128 v[214:217], v154 offset:56320
	global_load_lds_dwordx4 v[218:219], off
	s_add_i32 m0, s48, 0x2000
	s_add_u32 s46, s46, 0x40080
	v_lshl_add_u64 v[218:219], v[220:221], 0, s[16:17]
	s_addc_u32 s47, s47, 0
	s_add_i32 s48, s68, s52
	global_load_lds_dwordx4 v[218:219], off
	v_lshl_add_u64 v[218:219], s[46:47], 0, v[132:133]
	s_mov_b32 m0, s48
	s_nop 0
	global_load_lds_dwordx4 v[218:219], off
	v_lshl_add_u64 v[218:219], s[46:47], 0, v[136:137]
	s_add_i32 m0, s48, 0x2000
	s_nop 0
	global_load_lds_dwordx4 v[218:219], off
	v_lshl_add_u64 v[218:219], v[222:223], 0, s[16:17]
	s_mov_b32 m0, s57
	s_nop 0
	global_load_lds_dwordx4 v[218:219], off
	v_lshl_add_u64 v[218:219], v[224:225], 0, s[16:17]
	s_mov_b32 m0, s58
	s_nop 0
	global_load_lds_dwordx4 v[218:219], off
	s_waitcnt vmcnt(8)
	s_waitcnt lgkmcnt(0)
	s_barrier
	s_setprio 1
	v_mfma_f32_16x16x32_bf16 v[62:65], v[146:149], v[186:189], v[62:65]
	v_mfma_f32_16x16x32_bf16 v[58:61], v[160:163], v[186:189], v[58:61]
	v_mfma_f32_16x16x32_bf16 v[46:49], v[146:149], v[194:197], v[46:49]
	v_mfma_f32_16x16x32_bf16 v[42:45], v[160:163], v[194:197], v[42:45]
	v_mfma_f32_16x16x32_bf16 v[30:33], v[146:149], v[202:205], v[30:33]
	v_mfma_f32_16x16x32_bf16 v[26:29], v[160:163], v[202:205], v[26:29]
	v_mfma_f32_16x16x32_bf16 v[14:17], v[146:149], v[210:213], v[14:17]
	v_mfma_f32_16x16x32_bf16 v[10:13], v[160:163], v[210:213], v[10:13]
	v_mfma_f32_16x16x32_bf16 v[62:65], v[156:159], v[190:193], v[62:65]
	v_mfma_f32_16x16x32_bf16 v[58:61], v[164:167], v[190:193], v[58:61]
	v_mfma_f32_16x16x32_bf16 v[46:49], v[156:159], v[198:201], v[46:49]
	v_mfma_f32_16x16x32_bf16 v[42:45], v[164:167], v[198:201], v[42:45]
	v_mfma_f32_16x16x32_bf16 v[30:33], v[156:159], v[206:209], v[30:33]
	v_mfma_f32_16x16x32_bf16 v[26:29], v[164:167], v[206:209], v[26:29]
	v_mfma_f32_16x16x32_bf16 v[14:17], v[156:159], v[214:217], v[14:17]
	v_mfma_f32_16x16x32_bf16 v[10:13], v[164:167], v[214:217], v[10:13]
	v_mfma_f32_16x16x32_bf16 v[54:57], v[168:171], v[186:189], v[54:57]
	v_mfma_f32_16x16x32_bf16 v[50:53], v[176:179], v[186:189], v[50:53]
	v_mfma_f32_16x16x32_bf16 v[38:41], v[168:171], v[194:197], v[38:41]
	v_mfma_f32_16x16x32_bf16 v[34:37], v[176:179], v[194:197], v[34:37]
	v_mfma_f32_16x16x32_bf16 v[22:25], v[168:171], v[202:205], v[22:25]
	v_mfma_f32_16x16x32_bf16 v[18:21], v[176:179], v[202:205], v[18:21]
	v_mfma_f32_16x16x32_bf16 v[6:9], v[168:171], v[210:213], v[6:9]
	v_mfma_f32_16x16x32_bf16 v[2:5], v[176:179], v[210:213], v[2:5]
	v_mfma_f32_16x16x32_bf16 v[54:57], v[172:175], v[190:193], v[54:57]
	v_mfma_f32_16x16x32_bf16 v[50:53], v[180:183], v[190:193], v[50:53]
	v_mfma_f32_16x16x32_bf16 v[38:41], v[172:175], v[198:201], v[38:41]
	v_mfma_f32_16x16x32_bf16 v[34:37], v[180:183], v[198:201], v[34:37]
	v_mfma_f32_16x16x32_bf16 v[22:25], v[172:175], v[206:209], v[22:25]
	v_mfma_f32_16x16x32_bf16 v[18:21], v[180:183], v[206:209], v[18:21]
	v_mfma_f32_16x16x32_bf16 v[6:9], v[172:175], v[214:217], v[6:9]
	v_mfma_f32_16x16x32_bf16 v[2:5], v[180:183], v[214:217], v[2:5]
	s_setprio 0
	s_barrier
	s_add_i32 s66, s66, 2
	s_add_u32 s44, s44, 0x100
	s_addc_u32 s45, s45, 0
	s_add_u32 s64, s64, 0x100
	s_addc_u32 s65, s65, 0
	s_cmp_gt_u32 s66, 13
	s_cbranch_scc0 .LBB0_1133
	s_mov_b32 s99, 1
	s_and_b64 vcc, exec, s[18:19]
	s_cbranch_vccz .LBB0_1136
	s_barrier

; #define PG8_STAGE(bufoff, gbase, voff) do { _Pragma("unroll") for (int _i = 0; _i < 2; ++_i) \
;         __builtin_amdgcn_global_load_lds((const unsigned*)((const char*)(gbase) + (voff)[_i]), (LAS unsigned*)(lds + (bufoff) + ldsw + _i * 8192), 16, 0, 0); } while (0)
; #define PG8_LDA(dst, b, h) do { _Pragma("unroll") for (int m = 0; m < 4; ++m) _Pragma("unroll") for (int k = 0; k < 2; ++k) dst[m][k] = *(const LAS bf16x8*)(lds + PG8_SA(b, h) + aoff + m * 2048 + k * 1024); } while (0)
; #define PG8_LDB(dst, b, h) do { _Pragma("unroll") for (int n = 0; n < 2; ++n) _Pragma("unroll") for (int k = 0; k < 2; ++k) dst[n][k] = *(const LAS bf16x8*)(lds + PG8_SB(b, h) + boff + n * 2048 + k * 1024); } while (0)
; #define PG8_MMA(ai, bj, At, Bt) do { __builtin_amdgcn_s_setprio(1); _Pragma("unroll") for (int m = 0; m < 4; ++m) _Pragma("unroll") for (int n = 0; n < 2; ++n) _Pragma("unroll") for (int k = 0; k < 2; ++k) \
;         acc[ai][bj][m][n] = __builtin_amdgcn_mfma_f32_16x16x32_bf16(Bt[n][k], At[m][k], acc[ai][bj][m][n], 0, 0, 0); __builtin_amdgcn_s_setprio(0); } while (0)
; #define PG8_WAIT_V(n) asm volatile("s_waitcnt vmcnt(" #n ")" ::: "memory")
; #define PG8_WAIT_L(n) asm volatile("s_waitcnt lgkmcnt(" #n ")" ::: "memory")
; #define PG8_BAR __builtin_amdgcn_s_barrier()
; #define PG8_SCHED __builtin_amdgcn_sched_barrier(0)
; template <class Epi, class Sched>
; DI void gemm_phase(LAS unsigned char* lds, const Gemm g, const Sched& S, const Epi& E) {
;     ...
;             PG8_LDB(B0, 0, 0); PG8_LDB(B1, 0, 1); PG8_SCHED; PG8_LDA(At, 0, 0); PG8_STAGE(PG8_SA(1, 1), a1 + hstepA, voffA);
;             PG8_WAIT_V(8); PG8_WAIT_L(0); PG8_BAR; PG8_MMA(0, 0, At, B0); PG8_MMA(0, 1, At, B1); PG8_BAR; PG8_SCHED;
;             PG8_LDA(At, 0, 1); PG8_STAGE(PG8_SB(0, 0), b2, voffB); PG8_STAGE(PG8_SB(0, 1), b2 + hstepB, voffB); PG8_STAGE(PG8_SA(0, 0), a2, voffA);
;             PG8_WAIT_V(8); PG8_WAIT_L(0); PG8_BAR; PG8_MMA(1, 0, At, B0); PG8_MMA(1, 1, At, B1); PG8_BAR; PG8_SCHED;
.LBB0_1331:
	ds_read_b128 v[144:147], v151
	ds_read_b128 v[154:157], v151 offset:1024
	ds_read_b128 v[158:161], v151 offset:2048
	ds_read_b128 v[162:165], v151 offset:3072
	ds_read_b128 v[166:169], v152
	ds_read_b128 v[170:173], v152 offset:1024
	ds_read_b128 v[174:177], v152 offset:2048
	ds_read_b128 v[178:181], v152 offset:3072
	s_add_u32 s18, s16, 0xfff50080
	s_addc_u32 s19, s17, -1
	s_cmp_eq_u32 s47, 40
	s_cselect_b32 s21, s5, s19
	s_cselect_b32 s20, s4, s18
	s_cselect_b32 s19, s15, s46
	s_cselect_b32 s18, s14, s45
	v_lshl_add_u64 v[214:215], s[16:17], 0, v[136:137]
	s_add_i32 m0, s28, 0xc000
	ds_read_b128 v[182:185], v153
	ds_read_b128 v[186:189], v153 offset:1024
	ds_read_b128 v[190:193], v153 offset:2048
	ds_read_b128 v[194:197], v153 offset:3072
	ds_read_b128 v[198:201], v153 offset:4096
	ds_read_b128 v[202:205], v153 offset:5120
	ds_read_b128 v[206:209], v153 offset:6144
	ds_read_b128 v[210:213], v153 offset:7168
	global_load_lds_dwordx4 v[214:215], off
	v_lshl_add_u64 v[214:215], s[16:17], 0, v[138:139]
	s_add_i32 m0, s28, 0xe000
	s_nop 0
	global_load_lds_dwordx4 v[214:215], off
	s_waitcnt vmcnt(8)
	s_waitcnt lgkmcnt(0)
	s_barrier
	s_setprio 1
	v_mfma_f32_16x16x32_bf16 v[124:127], v[144:147], v[182:185], v[124:127]
	v_mfma_f32_16x16x32_bf16 v[120:123], v[158:161], v[182:185], v[120:123]
	v_mfma_f32_16x16x32_bf16 v[108:111], v[144:147], v[190:193], v[108:111]
	v_mfma_f32_16x16x32_bf16 v[104:107], v[158:161], v[190:193], v[104:107]
	v_mfma_f32_16x16x32_bf16 v[92:95], v[144:147], v[198:201], v[92:95]
	v_mfma_f32_16x16x32_bf16 v[88:91], v[158:161], v[198:201], v[88:91]
	v_mfma_f32_16x16x32_bf16 v[76:79], v[144:147], v[206:209], v[76:79]
	v_mfma_f32_16x16x32_bf16 v[72:75], v[158:161], v[206:209], v[72:75]
	v_mfma_f32_16x16x32_bf16 v[124:127], v[154:157], v[186:189], v[124:127]
	v_mfma_f32_16x16x32_bf16 v[120:123], v[162:165], v[186:189], v[120:123]
	v_mfma_f32_16x16x32_bf16 v[108:111], v[154:157], v[194:197], v[108:111]
	v_mfma_f32_16x16x32_bf16 v[104:107], v[162:165], v[194:197], v[104:107]
	v_mfma_f32_16x16x32_bf16 v[92:95], v[154:157], v[202:205], v[92:95]
	v_mfma_f32_16x16x32_bf16 v[88:91], v[162:165], v[202:205], v[88:91]
	v_mfma_f32_16x16x32_bf16 v[76:79], v[154:157], v[210:213], v[76:79]
	v_mfma_f32_16x16x32_bf16 v[72:75], v[162:165], v[210:213], v[72:75]
	v_mfma_f32_16x16x32_bf16 v[116:119], v[166:169], v[182:185], v[116:119]
	v_mfma_f32_16x16x32_bf16 v[112:115], v[174:177], v[182:185], v[112:115]
	v_mfma_f32_16x16x32_bf16 v[100:103], v[166:169], v[190:193], v[100:103]
	v_mfma_f32_16x16x32_bf16 v[96:99], v[174:177], v[190:193], v[96:99]
	v_mfma_f32_16x16x32_bf16 v[84:87], v[166:169], v[198:201], v[84:87]
	v_mfma_f32_16x16x32_bf16 v[80:83], v[174:177], v[198:201], v[80:83]
	v_mfma_f32_16x16x32_bf16 v[68:71], v[166:169], v[206:209], v[68:71]
	v_mfma_f32_16x16x32_bf16 v[64:67], v[174:177], v[206:209], v[64:67]
	v_mfma_f32_16x16x32_bf16 v[116:119], v[170:173], v[186:189], v[116:119]
	v_mfma_f32_16x16x32_bf16 v[112:115], v[178:181], v[186:189], v[112:115]
	v_mfma_f32_16x16x32_bf16 v[100:103], v[170:173], v[194:197], v[100:103]
	v_mfma_f32_16x16x32_bf16 v[96:99], v[178:181], v[194:197], v[96:99]
	v_mfma_f32_16x16x32_bf16 v[84:87], v[170:173], v[202:205], v[84:87]
	v_mfma_f32_16x16x32_bf16 v[80:83], v[178:181], v[202:205], v[80:83]
	v_mfma_f32_16x16x32_bf16 v[68:71], v[170:173], v[210:213], v[68:71]
	v_mfma_f32_16x16x32_bf16 v[64:67], v[178:181], v[210:213], v[64:67]
	s_setprio 0
	s_barrier
	s_add_i32 s48, s39, s27
	v_lshl_add_u64 v[214:215], s[18:19], 0, v[130:131]
	s_mov_b32 m0, s48
	ds_read_b128 v[182:185], v153 offset:16384
	ds_read_b128 v[186:189], v153 offset:17408
	ds_read_b128 v[190:193], v153 offset:18432
	ds_read_b128 v[194:197], v153 offset:19456
	ds_read_b128 v[198:201], v153 offset:20480
	ds_read_b128 v[202:205], v153 offset:21504
	ds_read_b128 v[206:209], v153 offset:22528
	ds_read_b128 v[210:213], v153 offset:23552
	global_load_lds_dwordx4 v[214:215], off
	s_add_i32 m0, s48, 0x2000
	s_add_u32 s48, s18, 0xb0000
	v_lshl_add_u64 v[216:217], s[18:19], 0, v[134:135]
	s_addc_u32 s49, s19, 0
	s_add_i32 s50, s40, s27
	global_load_lds_dwordx4 v[216:217], off
	v_lshl_add_u64 v[218:219], s[48:49], 0, v[130:131]
	s_mov_b32 m0, s50
	v_lshl_add_u64 v[220:221], s[20:21], 0, v[132:133]
	global_load_lds_dwordx4 v[218:219], off
	v_lshl_add_u64 v[218:219], s[48:49], 0, v[134:135]
	s_add_i32 m0, s50, 0x2000
	s_nop 0
	global_load_lds_dwordx4 v[218:219], off
	v_lshl_add_u64 v[218:219], s[20:21], 0, v[128:129]
	s_mov_b32 m0, s28
	s_nop 0
	global_load_lds_dwordx4 v[218:219], off
	s_mov_b32 m0, s29
	s_nop 0
	global_load_lds_dwordx4 v[220:221], off
	s_waitcnt vmcnt(8)
	s_waitcnt lgkmcnt(0)
	s_barrier
; #define PG8_STAGE(bufoff, gbase, voff) do { _Pragma("unroll") for (int _i = 0; _i < 2; ++_i) \
;         __builtin_amdgcn_global_load_lds((const unsigned*)((const char*)(gbase) + (voff)[_i]), (LAS unsigned*)(lds + (bufoff) + ldsw + _i * 8192), 16, 0, 0); } while (0)
; #define PG8_LDA(dst, b, h) do { _Pragma("unroll") for (int m = 0; m < 4; ++m) _Pragma("unroll") for (int k = 0; k < 2; ++k) dst[m][k] = *(const LAS bf16x8*)(lds + PG8_SA(b, h) + aoff + m * 2048 + k * 1024); } while (0)
; #define PG8_LDB(dst, b, h) do { _Pragma("unroll") for (int n = 0; n < 2; ++n) _Pragma("unroll") for (int k = 0; k < 2; ++k) dst[n][k] = *(const LAS bf16x8*)(lds + PG8_SB(b, h) + boff + n * 2048 + k * 1024); } while (0)
; #define PG8_MMA(ai, bj, At, Bt) do { __builtin_amdgcn_s_setprio(1); _Pragma("unroll") for (int m = 0; m < 4; ++m) _Pragma("unroll") for (int n = 0; n < 2; ++n) _Pragma("unroll") for (int k = 0; k < 2; ++k) \
;         acc[ai][bj][m][n] = __builtin_amdgcn_mfma_f32_16x16x32_bf16(Bt[n][k], At[m][k], acc[ai][bj][m][n], 0, 0, 0); __builtin_amdgcn_s_setprio(0); } while (0)
; #define PG8_WAIT_V(n) asm volatile("s_waitcnt vmcnt(" #n ")" ::: "memory")
; #define PG8_WAIT_L(n) asm volatile("s_waitcnt lgkmcnt(" #n ")" ::: "memory")
; #define PG8_BAR __builtin_amdgcn_s_barrier()
; #define PG8_SCHED __builtin_amdgcn_sched_barrier(0)
; template <class Epi, class Sched>
; DI void gemm_phase(LAS unsigned char* lds, const Gemm g, const Sched& S, const Epi& E) {
;     ...
;             PG8_WAIT_V(8); PG8_WAIT_L(0); PG8_BAR; PG8_MMA(1, 0, At, B0); PG8_MMA(1, 1, At, B1); PG8_BAR; PG8_SCHED;
;             PG8_LDB(B0, 1, 0); PG8_LDB(B1, 1, 1); PG8_SCHED; PG8_LDA(At, 1, 0); PG8_STAGE(PG8_SA(0, 1), a2 + hstepA, voffA);
;             PG8_WAIT_V(8); PG8_WAIT_L(0); PG8_BAR; PG8_MMA(0, 0, At, B0); PG8_MMA(0, 1, At, B1); PG8_BAR; PG8_SCHED;
	s_setprio 1
	v_mfma_f32_16x16x32_bf16 v[60:63], v[144:147], v[182:185], v[60:63]
	v_mfma_f32_16x16x32_bf16 v[56:59], v[158:161], v[182:185], v[56:59]
	v_mfma_f32_16x16x32_bf16 v[44:47], v[144:147], v[190:193], v[44:47]
	v_mfma_f32_16x16x32_bf16 v[40:43], v[158:161], v[190:193], v[40:43]
	v_mfma_f32_16x16x32_bf16 v[28:31], v[144:147], v[198:201], v[28:31]
	v_mfma_f32_16x16x32_bf16 v[24:27], v[158:161], v[198:201], v[24:27]
	v_mfma_f32_16x16x32_bf16 v[12:15], v[144:147], v[206:209], v[12:15]
	v_mfma_f32_16x16x32_bf16 v[8:11], v[158:161], v[206:209], v[8:11]
	v_mfma_f32_16x16x32_bf16 v[60:63], v[154:157], v[186:189], v[60:63]
	v_mfma_f32_16x16x32_bf16 v[56:59], v[162:165], v[186:189], v[56:59]
	v_mfma_f32_16x16x32_bf16 v[44:47], v[154:157], v[194:197], v[44:47]
	v_mfma_f32_16x16x32_bf16 v[40:43], v[162:165], v[194:197], v[40:43]
	v_mfma_f32_16x16x32_bf16 v[28:31], v[154:157], v[202:205], v[28:31]
	v_mfma_f32_16x16x32_bf16 v[24:27], v[162:165], v[202:205], v[24:27]
	v_mfma_f32_16x16x32_bf16 v[12:15], v[154:157], v[210:213], v[12:15]
	v_mfma_f32_16x16x32_bf16 v[8:11], v[162:165], v[210:213], v[8:11]
	v_mfma_f32_16x16x32_bf16 v[52:55], v[166:169], v[182:185], v[52:55]
	v_mfma_f32_16x16x32_bf16 v[48:51], v[174:177], v[182:185], v[48:51]
	v_mfma_f32_16x16x32_bf16 v[36:39], v[166:169], v[190:193], v[36:39]
	v_mfma_f32_16x16x32_bf16 v[32:35], v[174:177], v[190:193], v[32:35]
	v_mfma_f32_16x16x32_bf16 v[20:23], v[166:169], v[198:201], v[20:23]
	v_mfma_f32_16x16x32_bf16 v[16:19], v[174:177], v[198:201], v[16:19]
	v_mfma_f32_16x16x32_bf16 v[4:7], v[166:169], v[206:209], v[4:7]
	v_mfma_f32_16x16x32_bf16 v[0:3], v[174:177], v[206:209], v[0:3]
	v_mfma_f32_16x16x32_bf16 v[52:55], v[170:173], v[186:189], v[52:55]
	v_mfma_f32_16x16x32_bf16 v[48:51], v[178:181], v[186:189], v[48:51]
	v_mfma_f32_16x16x32_bf16 v[36:39], v[170:173], v[194:197], v[36:39]
	v_mfma_f32_16x16x32_bf16 v[32:35], v[178:181], v[194:197], v[32:35]
	v_mfma_f32_16x16x32_bf16 v[20:23], v[170:173], v[202:205], v[20:23]
	v_mfma_f32_16x16x32_bf16 v[16:19], v[178:181], v[202:205], v[16:19]
	v_mfma_f32_16x16x32_bf16 v[4:7], v[170:173], v[210:213], v[4:7]
	v_mfma_f32_16x16x32_bf16 v[0:3], v[178:181], v[210:213], v[0:3]
	s_setprio 0
	s_barrier
	s_add_i32 s48, 0, 0x18000
	s_add_i32 s49, 0, 0x1c000
	v_add_u32_e32 v162, s48, v149
	v_add_u32_e32 v178, s49, v149
	ds_read_b128 v[144:147], v162
	ds_read_b128 v[154:157], v162 offset:1024
	ds_read_b128 v[158:161], v162 offset:2048
	ds_read_b128 v[162:165], v162 offset:3072
	ds_read_b128 v[166:169], v178
	ds_read_b128 v[170:173], v178 offset:1024
	ds_read_b128 v[174:177], v178 offset:2048
	ds_read_b128 v[178:181], v178 offset:3072
	s_add_u32 s20, s20, 0xb0000
	s_addc_u32 s21, s21, 0
	s_mov_b32 m0, s33
	v_lshl_add_u64 v[222:223], s[20:21], 0, v[128:129]
	ds_read_b128 v[182:185], v153 offset:32768
	ds_read_b128 v[186:189], v153 offset:33792
	ds_read_b128 v[190:193], v153 offset:34816
	ds_read_b128 v[194:197], v153 offset:35840
	ds_read_b128 v[198:201], v153 offset:36864
	ds_read_b128 v[202:205], v153 offset:37888
	ds_read_b128 v[206:209], v153 offset:38912
	ds_read_b128 v[210:213], v153 offset:39936
	global_load_lds_dwordx4 v[222:223], off
	v_lshl_add_u64 v[222:223], s[20:21], 0, v[132:133]
	s_mov_b32 m0, s34
	s_nop 0
	global_load_lds_dwordx4 v[222:223], off
	s_waitcnt vmcnt(8)
	s_waitcnt lgkmcnt(0)
	s_barrier
	s_setprio 1
	v_mfma_f32_16x16x32_bf16 v[124:127], v[144:147], v[182:185], v[124:127]
	v_mfma_f32_16x16x32_bf16 v[120:123], v[158:161], v[182:185], v[120:123]
	v_mfma_f32_16x16x32_bf16 v[108:111], v[144:147], v[190:193], v[108:111]
	v_mfma_f32_16x16x32_bf16 v[104:107], v[158:161], v[190:193], v[104:107]
	v_mfma_f32_16x16x32_bf16 v[92:95], v[144:147], v[198:201], v[92:95]
	v_mfma_f32_16x16x32_bf16 v[88:91], v[158:161], v[198:201], v[88:91]
	v_mfma_f32_16x16x32_bf16 v[76:79], v[144:147], v[206:209], v[76:79]
	v_mfma_f32_16x16x32_bf16 v[72:75], v[158:161], v[206:209], v[72:75]
	v_mfma_f32_16x16x32_bf16 v[124:127], v[154:157], v[186:189], v[124:127]
	v_mfma_f32_16x16x32_bf16 v[120:123], v[162:165], v[186:189], v[120:123]
	v_mfma_f32_16x16x32_bf16 v[108:111], v[154:157], v[194:197], v[108:111]
	v_mfma_f32_16x16x32_bf16 v[104:107], v[162:165], v[194:197], v[104:107]
	v_mfma_f32_16x16x32_bf16 v[92:95], v[154:157], v[202:205], v[92:95]
	v_mfma_f32_16x16x32_bf16 v[88:91], v[162:165], v[202:205], v[88:91]
	v_mfma_f32_16x16x32_bf16 v[76:79], v[154:157], v[210:213], v[76:79]
	v_mfma_f32_16x16x32_bf16 v[72:75], v[162:165], v[210:213], v[72:75]
	v_mfma_f32_16x16x32_bf16 v[116:119], v[166:169], v[182:185], v[116:119]
	v_mfma_f32_16x16x32_bf16 v[112:115], v[174:177], v[182:185], v[112:115]
	v_mfma_f32_16x16x32_bf16 v[100:103], v[166:169], v[190:193], v[100:103]
	v_mfma_f32_16x16x32_bf16 v[96:99], v[174:177], v[190:193], v[96:99]
	v_mfma_f32_16x16x32_bf16 v[84:87], v[166:169], v[198:201], v[84:87]
	v_mfma_f32_16x16x32_bf16 v[80:83], v[174:177], v[198:201], v[80:83]
	v_mfma_f32_16x16x32_bf16 v[68:71], v[166:169], v[206:209], v[68:71]
	v_mfma_f32_16x16x32_bf16 v[64:67], v[174:177], v[206:209], v[64:67]
	v_mfma_f32_16x16x32_bf16 v[116:119], v[170:173], v[186:189], v[116:119]
	v_mfma_f32_16x16x32_bf16 v[112:115], v[178:181], v[186:189], v[112:115]
	v_mfma_f32_16x16x32_bf16 v[100:103], v[170:173], v[194:197], v[100:103]
	v_mfma_f32_16x16x32_bf16 v[96:99], v[178:181], v[194:197], v[96:99]
	v_mfma_f32_16x16x32_bf16 v[84:87], v[170:173], v[202:205], v[84:87]
	v_mfma_f32_16x16x32_bf16 v[80:83], v[178:181], v[202:205], v[80:83]
	v_mfma_f32_16x16x32_bf16 v[68:71], v[170:173], v[210:213], v[68:71]
	v_mfma_f32_16x16x32_bf16 v[64:67], v[178:181], v[210:213], v[64:67]
	s_setprio 0
	s_barrier
; #define PG8_STAGE(bufoff, gbase, voff) do { _Pragma("unroll") for (int _i = 0; _i < 2; ++_i) \
;         __builtin_amdgcn_global_load_lds((const unsigned*)((const char*)(gbase) + (voff)[_i]), (LAS unsigned*)(lds + (bufoff) + ldsw + _i * 8192), 16, 0, 0); } while (0)
; #define PG8_LDA(dst, b, h) do { _Pragma("unroll") for (int m = 0; m < 4; ++m) _Pragma("unroll") for (int k = 0; k < 2; ++k) dst[m][k] = *(const LAS bf16x8*)(lds + PG8_SA(b, h) + aoff + m * 2048 + k * 1024); } while (0)
; #define PG8_MMA(ai, bj, At, Bt) do { __builtin_amdgcn_s_setprio(1); _Pragma("unroll") for (int m = 0; m < 4; ++m) _Pragma("unroll") for (int n = 0; n < 2; ++n) _Pragma("unroll") for (int k = 0; k < 2; ++k) \
;         acc[ai][bj][m][n] = __builtin_amdgcn_mfma_f32_16x16x32_bf16(Bt[n][k], At[m][k], acc[ai][bj][m][n], 0, 0, 0); __builtin_amdgcn_s_setprio(0); } while (0)
; #define PG8_WAIT_V(n) asm volatile("s_waitcnt vmcnt(" #n ")" ::: "memory")
; #define PG8_WAIT_L(n) asm volatile("s_waitcnt lgkmcnt(" #n ")" ::: "memory")
; #define PG8_BAR __builtin_amdgcn_s_barrier()
; #define PG8_SCHED __builtin_amdgcn_sched_barrier(0)
;     DI void pre(Pre& pr, const pg8::Unit& u, int wr, int fr) const { load_rows(pr, ssq, u, wr, fr); }
;     DI void pre(Pre& pr, const pg8::Unit& u, int wr, int fr) const { load_rows(pr, ssq, u, wr, fr); }
; template <class Epi, class Sched>
; DI void gemm_phase(LAS unsigned char* lds, const Gemm g, const Sched& S, const Epi& E) {
;     ...
;             PG8_LDA(At, 1, 1); PG8_STAGE(PG8_SB(1, 0), b3, voffB); PG8_STAGE(PG8_SB(1, 1), b3 + hstepB, voffB); PG8_STAGE(PG8_SA(1, 0), a3, voffA);
;             PG8_WAIT_V(8); PG8_WAIT_L(0); PG8_BAR; PG8_MMA(1, 0, At, B0); PG8_MMA(1, 1, At, B1); PG8_BAR; PG8_SCHED;
;         }
;         if (wr == 0) PG8_BAR;
;         E(acc, cur, wr, wc, fr, fq, pre);
	s_add_i32 s20, s48, s27
	v_lshl_add_u64 v[214:215], v[214:215], 0, s[10:11]
	s_mov_b32 m0, s20
	ds_read_b128 v[182:185], v153 offset:49152
	ds_read_b128 v[186:189], v153 offset:50176
	ds_read_b128 v[190:193], v153 offset:51200
	ds_read_b128 v[194:197], v153 offset:52224
	ds_read_b128 v[198:201], v153 offset:53248
	ds_read_b128 v[202:205], v153 offset:54272
	ds_read_b128 v[206:209], v153 offset:55296
	ds_read_b128 v[210:213], v153 offset:56320
	global_load_lds_dwordx4 v[214:215], off
	s_add_i32 m0, s20, 0x2000
	s_add_u32 s18, s18, 0xb0080
	v_lshl_add_u64 v[214:215], v[216:217], 0, s[10:11]
	s_addc_u32 s19, s19, 0
	s_add_i32 s20, s49, s27
	global_load_lds_dwordx4 v[214:215], off
	v_lshl_add_u64 v[214:215], s[18:19], 0, v[130:131]
	s_mov_b32 m0, s20
	s_nop 0
	global_load_lds_dwordx4 v[214:215], off
	v_lshl_add_u64 v[214:215], s[18:19], 0, v[134:135]
	s_add_i32 m0, s20, 0x2000
	s_nop 0
	global_load_lds_dwordx4 v[214:215], off
	v_lshl_add_u64 v[214:215], v[218:219], 0, s[10:11]
	s_mov_b32 m0, s36
	s_nop 0
	global_load_lds_dwordx4 v[214:215], off
	v_lshl_add_u64 v[214:215], v[220:221], 0, s[10:11]
	s_mov_b32 m0, s37
	s_nop 0
	global_load_lds_dwordx4 v[214:215], off
	s_waitcnt vmcnt(8)
	s_waitcnt lgkmcnt(0)
	s_barrier
	s_setprio 1
	v_mfma_f32_16x16x32_bf16 v[60:63], v[144:147], v[182:185], v[60:63]
	v_mfma_f32_16x16x32_bf16 v[56:59], v[158:161], v[182:185], v[56:59]
	v_mfma_f32_16x16x32_bf16 v[44:47], v[144:147], v[190:193], v[44:47]
	v_mfma_f32_16x16x32_bf16 v[40:43], v[158:161], v[190:193], v[40:43]
	v_mfma_f32_16x16x32_bf16 v[28:31], v[144:147], v[198:201], v[28:31]
	v_mfma_f32_16x16x32_bf16 v[24:27], v[158:161], v[198:201], v[24:27]
	v_mfma_f32_16x16x32_bf16 v[12:15], v[144:147], v[206:209], v[12:15]
	v_mfma_f32_16x16x32_bf16 v[8:11], v[158:161], v[206:209], v[8:11]
	v_mfma_f32_16x16x32_bf16 v[60:63], v[154:157], v[186:189], v[60:63]
	v_mfma_f32_16x16x32_bf16 v[56:59], v[162:165], v[186:189], v[56:59]
	v_mfma_f32_16x16x32_bf16 v[44:47], v[154:157], v[194:197], v[44:47]
	v_mfma_f32_16x16x32_bf16 v[40:43], v[162:165], v[194:197], v[40:43]
	v_mfma_f32_16x16x32_bf16 v[28:31], v[154:157], v[202:205], v[28:31]
	v_mfma_f32_16x16x32_bf16 v[24:27], v[162:165], v[202:205], v[24:27]
	v_mfma_f32_16x16x32_bf16 v[12:15], v[154:157], v[210:213], v[12:15]
	v_mfma_f32_16x16x32_bf16 v[8:11], v[162:165], v[210:213], v[8:11]
	v_mfma_f32_16x16x32_bf16 v[52:55], v[166:169], v[182:185], v[52:55]
	v_mfma_f32_16x16x32_bf16 v[48:51], v[174:177], v[182:185], v[48:51]
	v_mfma_f32_16x16x32_bf16 v[36:39], v[166:169], v[190:193], v[36:39]
	v_mfma_f32_16x16x32_bf16 v[32:35], v[174:177], v[190:193], v[32:35]
	v_mfma_f32_16x16x32_bf16 v[20:23], v[166:169], v[198:201], v[20:23]
	v_mfma_f32_16x16x32_bf16 v[16:19], v[174:177], v[198:201], v[16:19]
	v_mfma_f32_16x16x32_bf16 v[4:7], v[166:169], v[206:209], v[4:7]
	v_mfma_f32_16x16x32_bf16 v[0:3], v[174:177], v[206:209], v[0:3]
	v_mfma_f32_16x16x32_bf16 v[52:55], v[170:173], v[186:189], v[52:55]
	v_mfma_f32_16x16x32_bf16 v[48:51], v[178:181], v[186:189], v[48:51]
	v_mfma_f32_16x16x32_bf16 v[36:39], v[170:173], v[194:197], v[36:39]
	v_mfma_f32_16x16x32_bf16 v[32:35], v[178:181], v[194:197], v[32:35]
	v_mfma_f32_16x16x32_bf16 v[20:23], v[170:173], v[202:205], v[20:23]
	v_mfma_f32_16x16x32_bf16 v[16:19], v[178:181], v[202:205], v[16:19]
	v_mfma_f32_16x16x32_bf16 v[4:7], v[170:173], v[210:213], v[4:7]
	v_mfma_f32_16x16x32_bf16 v[0:3], v[178:181], v[210:213], v[0:3]
	s_setprio 0
	s_barrier
	s_add_i32 s47, s47, 2
	s_add_u32 s16, s16, 0x100
	s_addc_u32 s17, s17, 0
	s_add_u32 s45, s45, 0x100
	s_addc_u32 s46, s46, 0
	s_cmp_gt_u32 s47, 41
	s_cbranch_scc0 .LBB0_1331
	s_mov_b32 s99, 1
	s_and_b64 vcc, exec, s[12:13]
	s_cbranch_vccz .LBB0_1334
	s_barrier
